# S5 output GEMM epilogue: per-group u loads issued up front into dead K-loop registers with counted waits (was 16 serialized load-wait pairs per tile)
# speedup vs baseline: 1.0035x; 1.0035x over previous
; __device__ __forceinline__ float fast_sigmoid(float v) { return __builtin_amdgcn_rcpf(1.0f + __builtin_amdgcn_exp2f(-v * LOG2E)); }
; __device__ __forceinline__ u32x4 pack8(f32x4 a, f32x4 b) { u32x4 w; w.x = cvt_pk_bf16(a[0], a[1]); w.y = cvt_pk_bf16(a[2], a[3]); w.z = cvt_pk_bf16(b[0], b[1]); w.w = cvt_pk_bf16(b[2], b[3]); return w; }
; __device__ __forceinline__ void unpack8(u32x4 w, f32x4& a, f32x4& b) { a = (f32x4){bf_lo(w.x), bf_hi(w.x), bf_lo(w.y), bf_hi(w.y)}; b = (f32x4){bf_lo(w.z), bf_hi(w.z), bf_lo(w.w), bf_hi(w.w)}; }
;     __device__ __forceinline__ void operator()(Acc& acc, const Unit& u, int wr, int wc, int fr, int fq) const {
;         const int R0 = u.pm * BM + wr * 64 + fr, gg = u.pm >> 2, nb = (u.pn & 1) * BM + wc * 64 + 8 * fq;
; #pragma unroll
;         for (int bj = 0; bj < 2; ++bj) { const int np = nb + bj * BJ, i = np >> 4, c0 = np & 15;
;             const f32x4 d0 = *(const f32x4*)(dskip + gg * 16 + c0), d1 = *(const f32x4*)(dskip + gg * 16 + c0 + 4);
; #pragma unroll
;             for (int ai = 0; ai < 2; ++ai)
; #pragma unroll
;                 for (int m = 0; m < 4; ++m) { const int R = R0 + ai * HALF + m * 16; const int token = (R & (ROWS_G - 1)) * TCH + i;
;                     f32x4 u0, u1; unpack8(*(const u32x4*)(a2 + (size_t)R * K2 + i * 16 + c0), u0, u1);
;                     f32x4 y0 = acc[ai][bj][m][0] + d0 * u0, y1 = acc[ai][bj][m][1] + d1 * u1;
; #pragma unroll
;                     for (int e = 0; e < 4; ++e) { { const float y = y0[e]; const float t = 1.5957691216057308f * y * (1.0f + 0.044715f * y * y); y0[e] = y * fast_sigmoid(t); }
;                                                   { const float y = y1[e]; const float t = 1.5957691216057308f * y * (1.0f + 0.044715f * y * y); y1[e] = y * fast_sigmoid(t); } }
;                     *(u32x4*)(gbuf + (size_t)token * 512 + gg * 16 + c0) = pack8(y0, y1); } }
;     }
.LBB0_436:
	s_lshl_b32 s2, s30, 8
	s_and_b32 s12, s2, 0x100
	v_mov_b32_e32 v98, 0x1d0
	v_or_b32_e32 v177, s12, v174
	v_bitop3_b32 v98, s12, v98, v174 bitop3:0xc8
	v_readlane_b32 s12, v251, 44
	v_readlane_b32 s13, v251, 45
	v_lshl_add_u32 v179, s10, 8, v172
	s_lshl_b32 s2, s10, 2
	v_mov_b64_e32 v[170:171], s[12:13]
	s_movk_i32 s10, 0x500
	s_and_b32 s2, s2, -16
	v_lshlrev_b32_e32 v154, 5, v179
	v_mad_i64_i32 v[168:169], s[12:13], v179, s10, v[170:171]
	v_lshlrev_b32_e32 v98, 1, v98
	s_ashr_i32 s3, s2, 31
	v_and_b32_e32 v176, 0x79e0, v154
	v_lshl_add_u64 v[154:155], v[168:169], 0, v[98:99]
	v_mov_b32_e32 v165, v99
	v_lshl_add_u64 v[166:167], s[2:3], 2, v[158:159]
	v_lshl_add_u64 v[154:155], v[154:155], 0, v[164:165]
	global_load_dwordx4 v[74:77], v[166:167], off offset:16
	global_load_dwordx4 v[78:81], v[166:167], off
	global_load_dwordx4 v[180:183], v[154:155], off
	v_mov_b64_e32 v[212:213], v[154:155]
	s_mov_b32 s101, 0
	s_mov_b32 s100, 0x5000
	v_lshl_add_u64 v[184:185], v[212:213], 0, s[100:101]
	global_load_dwordx4 v[184:187], v[184:185], off
	s_mov_b32 s100, 0xa000
	v_lshl_add_u64 v[188:189], v[212:213], 0, s[100:101]
	global_load_dwordx4 v[188:191], v[188:189], off
	s_mov_b32 s100, 0xf000
	v_lshl_add_u64 v[192:193], v[212:213], 0, s[100:101]
	global_load_dwordx4 v[192:195], v[192:193], off
	s_mov_b32 s100, 0x28000
	v_lshl_add_u64 v[196:197], v[212:213], 0, s[100:101]
	global_load_dwordx4 v[196:199], v[196:197], off
	s_mov_b32 s100, 0x2d000
	v_lshl_add_u64 v[200:201], v[212:213], 0, s[100:101]
	global_load_dwordx4 v[200:203], v[200:201], off
	s_mov_b32 s100, 0x32000
	v_lshl_add_u64 v[204:205], v[212:213], 0, s[100:101]
	global_load_dwordx4 v[204:207], v[204:205], off
	s_mov_b32 s100, 0x37000
	v_lshl_add_u64 v[208:209], v[212:213], 0, s[100:101]
	global_load_dwordx4 v[208:211], v[208:209], off
	s_mov_b32 s100, 0x5000
	v_lshl_add_u64 v[220:221], v[212:213], 0, s[100:101]
	global_load_dwordx4 v[220:223], v[220:221], off offset:64
	s_mov_b32 s100, 0xa000
	v_lshl_add_u64 v[224:225], v[212:213], 0, s[100:101]
	global_load_dwordx4 v[224:227], v[224:225], off offset:64
	s_mov_b32 s100, 0xf000
	v_lshl_add_u64 v[228:229], v[212:213], 0, s[100:101]
	global_load_dwordx4 v[228:231], v[228:229], off offset:64
	s_mov_b32 s100, 0x28000
	v_lshl_add_u64 v[232:233], v[212:213], 0, s[100:101]
	global_load_dwordx4 v[232:235], v[232:233], off offset:64
	v_lshrrev_b32_e32 v178, 4, v177
	v_readlane_b32 s14, v253, 2
	v_readlane_b32 s15, v253, 3
	s_lshl_b64 s[12:13], s[2:3], 1
	s_and_b64 vcc, exec, s[70:71]
	s_waitcnt vmcnt(11)
	v_lshlrev_b32_e32 v154, 16, v180
	v_and_b32_e32 v155, 0xffff0000, v180
	v_lshlrev_b32_e32 v156, 16, v181
	v_and_b32_e32 v157, 0xffff0000, v181
	v_lshlrev_b32_e32 v180, 16, v182
	v_and_b32_e32 v181, 0xffff0000, v182
	v_pk_fma_f32 v[136:137], v[78:79], v[154:155], v[136:137]
	v_pk_fma_f32 v[156:157], v[80:81], v[156:157], v[138:139]
	v_pk_fma_f32 v[138:139], v[74:75], v[180:181], v[132:133]
	v_mul_f32_e32 v133, 0x3d372713, v136
	v_mul_f32_e32 v132, 0x3fcc422a, v136
	v_fma_f32 v133, v136, v133, 1.0
	v_mul_f32_e32 v154, 0x3d372713, v138
	v_mul_f32_e32 v132, v132, v133
	v_mul_f32_e32 v133, 0x3fcc422a, v138
	v_fma_f32 v154, v138, v154, 1.0
	v_mul_f32_e32 v133, v133, v154
	v_mul_f32_e32 v133, 0xbfb8aa3b, v133
	v_exp_f32_e32 v133, v133
	v_mul_f32_e32 v155, 0x3d372713, v137
	v_fma_f32 v155, v137, v155, 1.0
	v_mul_f32_e32 v132, 0xbfb8aa3b, v132
	v_add_f32_e32 v133, 1.0, v133
	v_rcp_f32_e32 v154, v133
	v_mul_f32_e32 v133, 0x3fcc422a, v137
	v_mul_f32_e32 v133, v133, v155
	v_mul_f32_e32 v133, 0xbfb8aa3b, v133
	v_exp_f32_e32 v132, v132
	v_exp_f32_e32 v133, v133
	v_lshlrev_b32_e32 v182, 16, v183
	v_and_b32_e32 v183, 0xffff0000, v183
	v_add_f32_e32 v132, 1.0, v132
	v_add_f32_e32 v133, 1.0, v133
	v_rcp_f32_e32 v132, v132
	v_rcp_f32_e32 v133, v133
	v_pk_fma_f32 v[134:135], v[76:77], v[182:183], v[134:135]
	v_pk_mul_f32 v[132:133], v[136:137], v[132:133]
	v_mul_f32_e32 v137, 0x3d372713, v139
	v_mul_f32_e32 v136, 0x3fcc422a, v139
	v_fma_f32 v137, v139, v137, 1.0
	v_mul_f32_e32 v136, v136, v137
	v_mul_f32_e32 v136, 0xbfb8aa3b, v136
	v_exp_f32_e32 v136, v136
	v_cvt_pk_bf16_f32 v132, v132, v133
	v_add_f32_e32 v136, 1.0, v136
	v_rcp_f32_e32 v155, v136
	s_nop 0
	v_pk_mul_f32 v[136:137], v[138:139], v[154:155]
	v_mul_f32_e32 v139, 0x3d372713, v156
	v_mul_f32_e32 v138, 0x3fcc422a, v156
	v_fma_f32 v139, v156, v139, 1.0
	v_mul_f32_e32 v138, v138, v139
	v_mul_f32_e32 v138, 0xbfb8aa3b, v138
	v_exp_f32_e32 v138, v138
	v_mul_f32_e32 v139, 0x3d372713, v134
	v_fma_f32 v139, v134, v139, 1.0
	v_mul_f32_e32 v155, 0x3d372713, v157
	v_add_f32_e32 v138, 1.0, v138
	v_rcp_f32_e32 v154, v138
	v_mul_f32_e32 v138, 0x3fcc422a, v134
	v_mul_f32_e32 v138, v138, v139
	v_mul_f32_e32 v139, 0x3fcc422a, v157
	v_fma_f32 v155, v157, v155, 1.0
	v_mul_f32_e32 v139, v139, v155
	v_mul_f32_e32 v139, 0xbfb8aa3b, v139
	v_exp_f32_e32 v139, v139
	v_mul_f32_e32 v138, 0xbfb8aa3b, v138
	v_exp_f32_e32 v138, v138
	v_add_f32_e32 v139, 1.0, v139
	v_rcp_f32_e32 v155, v139
	v_mul_f32_e32 v139, 0x3fcc422a, v135
	v_add_f32_e32 v138, 1.0, v138
	v_rcp_f32_e32 v138, v138
	v_pk_mul_f32 v[154:155], v[156:157], v[154:155]
	v_mul_f32_e32 v156, 0x3d372713, v135
	v_fma_f32 v156, v135, v156, 1.0
	v_mul_f32_e32 v139, v139, v156
	v_mul_f32_e32 v139, 0xbfb8aa3b, v139
	v_exp_f32_e32 v139, v139
	v_or_b32_e32 v156, v176, v178
	v_cvt_pk_bf16_f32 v133, v154, v155
	v_add_f32_e32 v139, 1.0, v139
	v_rcp_f32_e32 v139, v139
	s_nop 0
	v_pk_mul_f32 v[138:139], v[134:135], v[138:139]
	v_cvt_pk_bf16_f32 v134, v136, v137
	v_lshlrev_b32_e32 v136, 10, v156
	v_mov_b32_e32 v137, v99
	v_lshl_add_u64 v[136:137], s[14:15], 0, v[136:137]
	v_lshl_add_u64 v[136:137], v[136:137], 0, s[12:13]
	v_cvt_pk_bf16_f32 v135, v138, v139
	v_lshl_add_u64 v[136:137], v[136:137], 0, v[164:165]
	global_store_dwordx4 v[136:137], v[132:135], off
	s_nop 1
	v_or_b32_e32 v132, 16, v179
	v_lshlrev_b32_e32 v133, 5, v132
	v_and_b32_e32 v134, 0x7be0, v133
	v_mad_i64_i32 v[132:133], s[2:3], v132, s10, v[170:171]
	v_lshl_add_u64 v[136:137], v[132:133], 0, v[98:99]
	v_lshl_add_u64 v[136:137], v[136:137], 0, v[164:165]
	s_waitcnt vmcnt(11)
; __device__ __forceinline__ float fast_sigmoid(float v) { return __builtin_amdgcn_rcpf(1.0f + __builtin_amdgcn_exp2f(-v * LOG2E)); }
; __device__ __forceinline__ u32x4 pack8(f32x4 a, f32x4 b) { u32x4 w; w.x = cvt_pk_bf16(a[0], a[1]); w.y = cvt_pk_bf16(a[2], a[3]); w.z = cvt_pk_bf16(b[0], b[1]); w.w = cvt_pk_bf16(b[2], b[3]); return w; }
; __device__ __forceinline__ void unpack8(u32x4 w, f32x4& a, f32x4& b) { a = (f32x4){bf_lo(w.x), bf_hi(w.x), bf_lo(w.y), bf_hi(w.y)}; b = (f32x4){bf_lo(w.z), bf_hi(w.z), bf_lo(w.w), bf_hi(w.w)}; }
;     __device__ __forceinline__ void operator()(Acc& acc, const Unit& u, int wr, int wc, int fr, int fq) const {
;         const int R0 = u.pm * BM + wr * 64 + fr, gg = u.pm >> 2, nb = (u.pn & 1) * BM + wc * 64 + 8 * fq;
; #pragma unroll
;         for (int bj = 0; bj < 2; ++bj) { const int np = nb + bj * BJ, i = np >> 4, c0 = np & 15;
;             const f32x4 d0 = *(const f32x4*)(dskip + gg * 16 + c0), d1 = *(const f32x4*)(dskip + gg * 16 + c0 + 4);
; #pragma unroll
;             for (int ai = 0; ai < 2; ++ai)
; #pragma unroll
;                 for (int m = 0; m < 4; ++m) { const int R = R0 + ai * HALF + m * 16; const int token = (R & (ROWS_G - 1)) * TCH + i;
;                     f32x4 u0, u1; unpack8(*(const u32x4*)(a2 + (size_t)R * K2 + i * 16 + c0), u0, u1);
;                     f32x4 y0 = acc[ai][bj][m][0] + d0 * u0, y1 = acc[ai][bj][m][1] + d1 * u1;
; #pragma unroll
;                     for (int e = 0; e < 4; ++e) { { const float y = y0[e]; const float t = 1.5957691216057308f * y * (1.0f + 0.044715f * y * y); y0[e] = y * fast_sigmoid(t); }
;                                                   { const float y = y1[e]; const float t = 1.5957691216057308f * y * (1.0f + 0.044715f * y * y); y1[e] = y * fast_sigmoid(t); } }
;                     *(u32x4*)(gbuf + (size_t)token * 512 + gg * 16 + c0) = pack8(y0, y1); } }
;     }
	v_mov_b64_e32 v[136:137], v[184:185]
	v_mov_b64_e32 v[138:139], v[186:187]
	s_mov_b32 s100, 0x2d000
	v_lshl_add_u64 v[184:185], v[212:213], 0, s[100:101]
	global_load_dwordx4 v[184:187], v[184:185], off offset:64
	v_lshlrev_b32_e32 v154, 16, v136
	v_and_b32_e32 v155, 0xffff0000, v136
	v_lshlrev_b32_e32 v136, 16, v137
	v_and_b32_e32 v137, 0xffff0000, v137
	v_lshlrev_b32_e32 v156, 16, v138
	v_and_b32_e32 v157, 0xffff0000, v138
	v_pk_fma_f32 v[128:129], v[78:79], v[154:155], v[128:129]
	v_pk_fma_f32 v[136:137], v[80:81], v[136:137], v[130:131]
	v_pk_fma_f32 v[130:131], v[74:75], v[156:157], v[124:125]
	v_mul_f32_e32 v125, 0x3d372713, v128
	v_mul_f32_e32 v124, 0x3fcc422a, v128
	v_fma_f32 v125, v128, v125, 1.0
	v_mul_f32_e32 v135, 0x3d372713, v130
	v_mul_f32_e32 v124, v124, v125
	v_mul_f32_e32 v125, 0x3fcc422a, v130
	v_fma_f32 v135, v130, v135, 1.0
	v_mul_f32_e32 v125, v125, v135
	v_mul_f32_e32 v125, 0xbfb8aa3b, v125
	v_exp_f32_e32 v125, v125
	v_lshlrev_b32_e32 v138, 16, v139
	v_and_b32_e32 v139, 0xffff0000, v139
	v_mul_f32_e32 v135, 0x3d372713, v129
	v_add_f32_e32 v125, 1.0, v125
	v_pk_fma_f32 v[126:127], v[76:77], v[138:139], v[126:127]
	v_rcp_f32_e32 v138, v125
	v_mul_f32_e32 v125, 0x3fcc422a, v129
	v_fma_f32 v135, v129, v135, 1.0
	v_mul_f32_e32 v125, v125, v135
	v_mul_f32_e32 v124, 0xbfb8aa3b, v124
	v_mul_f32_e32 v125, 0xbfb8aa3b, v125
	v_exp_f32_e32 v124, v124
	v_exp_f32_e32 v125, v125
	v_mul_f32_e32 v135, 0x3d372713, v137
	v_fma_f32 v135, v137, v135, 1.0
	v_add_f32_e32 v124, 1.0, v124
	v_add_f32_e32 v125, 1.0, v125
	v_rcp_f32_e32 v124, v124
	v_rcp_f32_e32 v125, v125
	s_nop 0
	v_pk_mul_f32 v[124:125], v[128:129], v[124:125]
	v_mul_f32_e32 v129, 0x3d372713, v131
	v_mul_f32_e32 v128, 0x3fcc422a, v131
	v_fma_f32 v129, v131, v129, 1.0
	v_mul_f32_e32 v128, v128, v129
	v_mul_f32_e32 v128, 0xbfb8aa3b, v128
	v_exp_f32_e32 v128, v128
	v_cvt_pk_bf16_f32 v124, v124, v125
	v_add_f32_e32 v128, 1.0, v128
	v_rcp_f32_e32 v139, v128
	s_nop 0
	v_pk_mul_f32 v[128:129], v[130:131], v[138:139]
	v_mul_f32_e32 v131, 0x3d372713, v136
	v_mul_f32_e32 v130, 0x3fcc422a, v136
	v_fma_f32 v131, v136, v131, 1.0
	v_mul_f32_e32 v130, v130, v131
	v_mul_f32_e32 v130, 0xbfb8aa3b, v130
	v_exp_f32_e32 v130, v130
	v_mul_f32_e32 v131, 0x3d372713, v126
	v_fma_f32 v131, v126, v131, 1.0
	v_add_f32_e32 v130, 1.0, v130
	v_rcp_f32_e32 v138, v130
	v_mul_f32_e32 v130, 0x3fcc422a, v126
	v_mul_f32_e32 v130, v130, v131
	v_mul_f32_e32 v131, 0x3fcc422a, v137
	v_mul_f32_e32 v131, v131, v135
	v_mul_f32_e32 v131, 0xbfb8aa3b, v131
	v_exp_f32_e32 v131, v131
	v_mul_f32_e32 v135, 0x3d372713, v127
	v_fma_f32 v135, v127, v135, 1.0
	v_mul_f32_e32 v130, 0xbfb8aa3b, v130
	v_add_f32_e32 v131, 1.0, v131
	v_rcp_f32_e32 v139, v131
	v_mul_f32_e32 v131, 0x3fcc422a, v127
	v_mul_f32_e32 v131, v131, v135
	v_mul_f32_e32 v131, 0xbfb8aa3b, v131
	v_exp_f32_e32 v130, v130
	v_exp_f32_e32 v131, v131
	v_or_b32_e32 v135, v134, v178
	v_pk_mul_f32 v[136:137], v[136:137], v[138:139]
	v_add_f32_e32 v130, 1.0, v130
	v_add_f32_e32 v131, 1.0, v131
	v_rcp_f32_e32 v130, v130
	v_rcp_f32_e32 v131, v131
	v_cvt_pk_bf16_f32 v125, v136, v137
	v_pk_mul_f32 v[130:131], v[126:127], v[130:131]
	v_cvt_pk_bf16_f32 v126, v128, v129
	v_lshlrev_b32_e32 v128, 10, v135
	v_mov_b32_e32 v129, v99
	v_lshl_add_u64 v[128:129], s[14:15], 0, v[128:129]
	v_lshl_add_u64 v[128:129], v[128:129], 0, s[12:13]
	v_cvt_pk_bf16_f32 v127, v130, v131
	v_lshl_add_u64 v[128:129], v[128:129], 0, v[164:165]
	global_store_dwordx4 v[128:129], v[124:127], off
	s_nop 1
	v_or_b32_e32 v124, 32, v179
	v_lshlrev_b32_e32 v125, 5, v124
	v_and_b32_e32 v126, 0x7de0, v125
	v_mad_i64_i32 v[124:125], s[2:3], v124, s10, v[170:171]
	v_lshl_add_u64 v[128:129], v[124:125], 0, v[98:99]
	v_lshl_add_u64 v[128:129], v[128:129], 0, v[164:165]
	s_waitcnt vmcnt(12)
	v_mov_b64_e32 v[128:129], v[188:189]
	v_mov_b64_e32 v[130:131], v[190:191]
	s_mov_b32 s100, 0x32000
	v_lshl_add_u64 v[188:189], v[212:213], 0, s[100:101]
	global_load_dwordx4 v[188:191], v[188:189], off offset:64
	v_lshlrev_b32_e32 v136, 16, v128
	v_and_b32_e32 v137, 0xffff0000, v128
	v_lshlrev_b32_e32 v128, 16, v129
	v_and_b32_e32 v129, 0xffff0000, v129
	v_lshlrev_b32_e32 v138, 16, v130
	v_and_b32_e32 v139, 0xffff0000, v130
	v_pk_fma_f32 v[120:121], v[78:79], v[136:137], v[120:121]
	v_pk_fma_f32 v[128:129], v[80:81], v[128:129], v[122:123]
	v_pk_fma_f32 v[122:123], v[74:75], v[138:139], v[116:117]
	v_mul_f32_e32 v117, 0x3d372713, v120
	v_mul_f32_e32 v116, 0x3fcc422a, v120
	v_fma_f32 v117, v120, v117, 1.0
	v_mul_f32_e32 v127, 0x3d372713, v122
	v_mul_f32_e32 v116, v116, v117
	v_mul_f32_e32 v117, 0x3fcc422a, v122
	v_fma_f32 v127, v122, v127, 1.0
	v_mul_f32_e32 v117, v117, v127
	v_mul_f32_e32 v117, 0xbfb8aa3b, v117
	v_exp_f32_e32 v117, v117
	v_lshlrev_b32_e32 v130, 16, v131
	v_and_b32_e32 v131, 0xffff0000, v131
	v_mul_f32_e32 v127, 0x3d372713, v121
	v_add_f32_e32 v117, 1.0, v117
	v_pk_fma_f32 v[118:119], v[76:77], v[130:131], v[118:119]
	v_rcp_f32_e32 v130, v117
	v_mul_f32_e32 v117, 0x3fcc422a, v121
	v_fma_f32 v127, v121, v127, 1.0
	v_mul_f32_e32 v117, v117, v127
	v_mul_f32_e32 v116, 0xbfb8aa3b, v116
	v_mul_f32_e32 v117, 0xbfb8aa3b, v117
	v_exp_f32_e32 v116, v116
	v_exp_f32_e32 v117, v117
	v_mul_f32_e32 v127, 0x3d372713, v129
	v_fma_f32 v127, v129, v127, 1.0
	v_add_f32_e32 v116, 1.0, v116
	v_add_f32_e32 v117, 1.0, v117
	v_rcp_f32_e32 v116, v116
	v_rcp_f32_e32 v117, v117
	s_nop 0
	v_pk_mul_f32 v[116:117], v[120:121], v[116:117]
	v_mul_f32_e32 v121, 0x3d372713, v123
	v_mul_f32_e32 v120, 0x3fcc422a, v123
	v_fma_f32 v121, v123, v121, 1.0
	v_mul_f32_e32 v120, v120, v121
	v_mul_f32_e32 v120, 0xbfb8aa3b, v120
	v_exp_f32_e32 v120, v120
; __device__ __forceinline__ float fast_sigmoid(float v) { return __builtin_amdgcn_rcpf(1.0f + __builtin_amdgcn_exp2f(-v * LOG2E)); }
; __device__ __forceinline__ u32x4 pack8(f32x4 a, f32x4 b) { u32x4 w; w.x = cvt_pk_bf16(a[0], a[1]); w.y = cvt_pk_bf16(a[2], a[3]); w.z = cvt_pk_bf16(b[0], b[1]); w.w = cvt_pk_bf16(b[2], b[3]); return w; }
; __device__ __forceinline__ void unpack8(u32x4 w, f32x4& a, f32x4& b) { a = (f32x4){bf_lo(w.x), bf_hi(w.x), bf_lo(w.y), bf_hi(w.y)}; b = (f32x4){bf_lo(w.z), bf_hi(w.z), bf_lo(w.w), bf_hi(w.w)}; }
;     __device__ __forceinline__ void operator()(Acc& acc, const Unit& u, int wr, int wc, int fr, int fq) const {
;         const int R0 = u.pm * BM + wr * 64 + fr, gg = u.pm >> 2, nb = (u.pn & 1) * BM + wc * 64 + 8 * fq;
; #pragma unroll
;         for (int bj = 0; bj < 2; ++bj) { const int np = nb + bj * BJ, i = np >> 4, c0 = np & 15;
;             const f32x4 d0 = *(const f32x4*)(dskip + gg * 16 + c0), d1 = *(const f32x4*)(dskip + gg * 16 + c0 + 4);
; #pragma unroll
;             for (int ai = 0; ai < 2; ++ai)
; #pragma unroll
;                 for (int m = 0; m < 4; ++m) { const int R = R0 + ai * HALF + m * 16; const int token = (R & (ROWS_G - 1)) * TCH + i;
;                     f32x4 u0, u1; unpack8(*(const u32x4*)(a2 + (size_t)R * K2 + i * 16 + c0), u0, u1);
;                     f32x4 y0 = acc[ai][bj][m][0] + d0 * u0, y1 = acc[ai][bj][m][1] + d1 * u1;
; #pragma unroll
;                     for (int e = 0; e < 4; ++e) { { const float y = y0[e]; const float t = 1.5957691216057308f * y * (1.0f + 0.044715f * y * y); y0[e] = y * fast_sigmoid(t); }
;                                                   { const float y = y1[e]; const float t = 1.5957691216057308f * y * (1.0f + 0.044715f * y * y); y1[e] = y * fast_sigmoid(t); } }
;                     *(u32x4*)(gbuf + (size_t)token * 512 + gg * 16 + c0) = pack8(y0, y1); } }
;     }
	v_cvt_pk_bf16_f32 v116, v116, v117
	v_add_f32_e32 v120, 1.0, v120
	v_rcp_f32_e32 v131, v120
	s_nop 0
	v_pk_mul_f32 v[120:121], v[122:123], v[130:131]
	v_mul_f32_e32 v123, 0x3d372713, v128
	v_mul_f32_e32 v122, 0x3fcc422a, v128
	v_fma_f32 v123, v128, v123, 1.0
	v_mul_f32_e32 v122, v122, v123
	v_mul_f32_e32 v122, 0xbfb8aa3b, v122
	v_exp_f32_e32 v122, v122
	v_mul_f32_e32 v123, 0x3d372713, v118
	v_fma_f32 v123, v118, v123, 1.0
	v_add_f32_e32 v122, 1.0, v122
	v_rcp_f32_e32 v130, v122
	v_mul_f32_e32 v122, 0x3fcc422a, v118
	v_mul_f32_e32 v122, v122, v123
	v_mul_f32_e32 v123, 0x3fcc422a, v129
	v_mul_f32_e32 v123, v123, v127
	v_mul_f32_e32 v123, 0xbfb8aa3b, v123
	v_exp_f32_e32 v123, v123
	v_mul_f32_e32 v127, 0x3d372713, v119
	v_fma_f32 v127, v119, v127, 1.0
	v_mul_f32_e32 v122, 0xbfb8aa3b, v122
	v_add_f32_e32 v123, 1.0, v123
	v_rcp_f32_e32 v131, v123
	v_mul_f32_e32 v123, 0x3fcc422a, v119
	v_mul_f32_e32 v123, v123, v127
	v_mul_f32_e32 v123, 0xbfb8aa3b, v123
	v_exp_f32_e32 v122, v122
	v_exp_f32_e32 v123, v123
	v_or_b32_e32 v127, v126, v178
	v_pk_mul_f32 v[128:129], v[128:129], v[130:131]
	v_add_f32_e32 v122, 1.0, v122
	v_add_f32_e32 v123, 1.0, v123
	v_rcp_f32_e32 v122, v122
	v_rcp_f32_e32 v123, v123
	v_cvt_pk_bf16_f32 v117, v128, v129
	v_pk_mul_f32 v[122:123], v[118:119], v[122:123]
	v_cvt_pk_bf16_f32 v118, v120, v121
	v_lshlrev_b32_e32 v120, 10, v127
	v_mov_b32_e32 v121, v99
	v_lshl_add_u64 v[120:121], s[14:15], 0, v[120:121]
	v_lshl_add_u64 v[120:121], v[120:121], 0, s[12:13]
	v_cvt_pk_bf16_f32 v119, v122, v123
	v_lshl_add_u64 v[120:121], v[120:121], 0, v[164:165]
	global_store_dwordx4 v[120:121], v[116:119], off
	s_nop 1
	v_or_b32_e32 v116, 48, v179
	v_lshlrev_b32_e32 v117, 5, v116
	v_and_b32_e32 v118, 0x7fe0, v117
	v_mad_i64_i32 v[116:117], s[2:3], v116, s10, v[170:171]
	v_lshl_add_u64 v[120:121], v[116:117], 0, v[98:99]
	v_lshl_add_u64 v[120:121], v[120:121], 0, v[164:165]
	s_waitcnt vmcnt(13)
	v_mov_b64_e32 v[120:121], v[192:193]
	v_mov_b64_e32 v[122:123], v[194:195]
	s_mov_b32 s100, 0x37000
	v_lshl_add_u64 v[192:193], v[212:213], 0, s[100:101]
	global_load_dwordx4 v[192:195], v[192:193], off offset:64
	v_lshlrev_b32_e32 v128, 16, v120
	v_and_b32_e32 v129, 0xffff0000, v120
	v_lshlrev_b32_e32 v120, 16, v121
	v_and_b32_e32 v121, 0xffff0000, v121
	v_lshlrev_b32_e32 v130, 16, v122
	v_and_b32_e32 v131, 0xffff0000, v122
	v_pk_fma_f32 v[112:113], v[78:79], v[128:129], v[112:113]
	v_pk_fma_f32 v[120:121], v[80:81], v[120:121], v[114:115]
	v_pk_fma_f32 v[114:115], v[74:75], v[130:131], v[108:109]
	v_mul_f32_e32 v109, 0x3d372713, v112
	v_mul_f32_e32 v108, 0x3fcc422a, v112
	v_fma_f32 v109, v112, v109, 1.0
	v_mul_f32_e32 v119, 0x3d372713, v114
	v_mul_f32_e32 v108, v108, v109
	v_mul_f32_e32 v109, 0x3fcc422a, v114
	v_fma_f32 v119, v114, v119, 1.0
	v_mul_f32_e32 v109, v109, v119
	v_mul_f32_e32 v109, 0xbfb8aa3b, v109
	v_exp_f32_e32 v109, v109
	v_lshlrev_b32_e32 v122, 16, v123
	v_and_b32_e32 v123, 0xffff0000, v123
	v_mul_f32_e32 v119, 0x3d372713, v113
	v_add_f32_e32 v109, 1.0, v109
	v_pk_fma_f32 v[110:111], v[76:77], v[122:123], v[110:111]
	v_rcp_f32_e32 v122, v109
	v_mul_f32_e32 v109, 0x3fcc422a, v113
	v_fma_f32 v119, v113, v119, 1.0
	v_mul_f32_e32 v109, v109, v119
	v_mul_f32_e32 v108, 0xbfb8aa3b, v108
	v_mul_f32_e32 v109, 0xbfb8aa3b, v109
	v_exp_f32_e32 v108, v108
	v_exp_f32_e32 v109, v109
	v_mul_f32_e32 v119, 0x3d372713, v121
	v_fma_f32 v119, v121, v119, 1.0
	v_add_f32_e32 v108, 1.0, v108
	v_add_f32_e32 v109, 1.0, v109
	v_rcp_f32_e32 v108, v108
	v_rcp_f32_e32 v109, v109
	s_nop 0
	v_pk_mul_f32 v[108:109], v[112:113], v[108:109]
	v_mul_f32_e32 v113, 0x3d372713, v115
	v_mul_f32_e32 v112, 0x3fcc422a, v115
	v_fma_f32 v113, v115, v113, 1.0
	v_mul_f32_e32 v112, v112, v113
	v_mul_f32_e32 v112, 0xbfb8aa3b, v112
	v_exp_f32_e32 v112, v112
	v_cvt_pk_bf16_f32 v108, v108, v109
	v_add_f32_e32 v112, 1.0, v112
	v_rcp_f32_e32 v123, v112
	s_nop 0
	v_pk_mul_f32 v[112:113], v[114:115], v[122:123]
	v_mul_f32_e32 v115, 0x3d372713, v120
	v_mul_f32_e32 v114, 0x3fcc422a, v120
	v_fma_f32 v115, v120, v115, 1.0
	v_mul_f32_e32 v114, v114, v115
	v_mul_f32_e32 v114, 0xbfb8aa3b, v114
	v_exp_f32_e32 v114, v114
	v_mul_f32_e32 v115, 0x3d372713, v110
	v_fma_f32 v115, v110, v115, 1.0
	v_add_f32_e32 v114, 1.0, v114
	v_rcp_f32_e32 v122, v114
	v_mul_f32_e32 v114, 0x3fcc422a, v110
	v_mul_f32_e32 v114, v114, v115
	v_mul_f32_e32 v115, 0x3fcc422a, v121
	v_mul_f32_e32 v115, v115, v119
	v_mul_f32_e32 v115, 0xbfb8aa3b, v115
	v_exp_f32_e32 v115, v115
	v_mul_f32_e32 v119, 0x3d372713, v111
	v_fma_f32 v119, v111, v119, 1.0
	v_mul_f32_e32 v114, 0xbfb8aa3b, v114
	v_add_f32_e32 v115, 1.0, v115
	v_rcp_f32_e32 v123, v115
	v_mul_f32_e32 v115, 0x3fcc422a, v111
	v_mul_f32_e32 v115, v115, v119
	v_mul_f32_e32 v115, 0xbfb8aa3b, v115
	v_exp_f32_e32 v114, v114
	v_exp_f32_e32 v115, v115
	v_or_b32_e32 v119, v118, v178
	v_pk_mul_f32 v[120:121], v[120:121], v[122:123]
	v_add_f32_e32 v114, 1.0, v114
	v_add_f32_e32 v115, 1.0, v115
	v_rcp_f32_e32 v114, v114
	v_rcp_f32_e32 v115, v115
	v_cvt_pk_bf16_f32 v109, v120, v121
	v_pk_mul_f32 v[114:115], v[110:111], v[114:115]
	v_cvt_pk_bf16_f32 v110, v112, v113
	v_lshlrev_b32_e32 v112, 10, v119
	v_mov_b32_e32 v113, v99
	v_lshl_add_u64 v[112:113], s[14:15], 0, v[112:113]
	v_lshl_add_u64 v[112:113], v[112:113], 0, s[12:13]
	v_cvt_pk_bf16_f32 v111, v114, v115
	v_lshl_add_u64 v[112:113], v[112:113], 0, v[164:165]
	global_store_dwordx4 v[112:113], v[108:111], off
	s_nop 1
	v_add_u32_e32 v108, 0x80, v179
	v_lshlrev_b32_e32 v109, 5, v108
	v_and_b32_e32 v110, 0x79e0, v109
	v_mad_i64_i32 v[108:109], s[2:3], v108, s10, v[170:171]
	v_lshl_add_u64 v[112:113], v[108:109], 0, v[98:99]
	v_lshl_add_u64 v[112:113], v[112:113], 0, v[164:165]
	s_waitcnt vmcnt(14)
; __device__ __forceinline__ float fast_sigmoid(float v) { return __builtin_amdgcn_rcpf(1.0f + __builtin_amdgcn_exp2f(-v * LOG2E)); }
; __device__ __forceinline__ u32x4 pack8(f32x4 a, f32x4 b) { u32x4 w; w.x = cvt_pk_bf16(a[0], a[1]); w.y = cvt_pk_bf16(a[2], a[3]); w.z = cvt_pk_bf16(b[0], b[1]); w.w = cvt_pk_bf16(b[2], b[3]); return w; }
; __device__ __forceinline__ void unpack8(u32x4 w, f32x4& a, f32x4& b) { a = (f32x4){bf_lo(w.x), bf_hi(w.x), bf_lo(w.y), bf_hi(w.y)}; b = (f32x4){bf_lo(w.z), bf_hi(w.z), bf_lo(w.w), bf_hi(w.w)}; }
;     __device__ __forceinline__ void operator()(Acc& acc, const Unit& u, int wr, int wc, int fr, int fq) const {
;         const int R0 = u.pm * BM + wr * 64 + fr, gg = u.pm >> 2, nb = (u.pn & 1) * BM + wc * 64 + 8 * fq;
; #pragma unroll
;         for (int bj = 0; bj < 2; ++bj) { const int np = nb + bj * BJ, i = np >> 4, c0 = np & 15;
;             const f32x4 d0 = *(const f32x4*)(dskip + gg * 16 + c0), d1 = *(const f32x4*)(dskip + gg * 16 + c0 + 4);
; #pragma unroll
;             for (int ai = 0; ai < 2; ++ai)
; #pragma unroll
;                 for (int m = 0; m < 4; ++m) { const int R = R0 + ai * HALF + m * 16; const int token = (R & (ROWS_G - 1)) * TCH + i;
;                     f32x4 u0, u1; unpack8(*(const u32x4*)(a2 + (size_t)R * K2 + i * 16 + c0), u0, u1);
;                     f32x4 y0 = acc[ai][bj][m][0] + d0 * u0, y1 = acc[ai][bj][m][1] + d1 * u1;
; #pragma unroll
;                     for (int e = 0; e < 4; ++e) { { const float y = y0[e]; const float t = 1.5957691216057308f * y * (1.0f + 0.044715f * y * y); y0[e] = y * fast_sigmoid(t); }
;                                                   { const float y = y1[e]; const float t = 1.5957691216057308f * y * (1.0f + 0.044715f * y * y); y1[e] = y * fast_sigmoid(t); } }
;                     *(u32x4*)(gbuf + (size_t)token * 512 + gg * 16 + c0) = pack8(y0, y1); } }
;     }
	v_mov_b64_e32 v[112:113], v[196:197]
	v_mov_b64_e32 v[114:115], v[198:199]
	v_lshlrev_b32_e32 v120, 16, v112
	v_and_b32_e32 v121, 0xffff0000, v112
	v_lshlrev_b32_e32 v112, 16, v113
	v_and_b32_e32 v113, 0xffff0000, v113
	v_lshlrev_b32_e32 v122, 16, v114
	v_and_b32_e32 v123, 0xffff0000, v114
	v_pk_fma_f32 v[104:105], v[78:79], v[120:121], v[104:105]
	v_pk_fma_f32 v[112:113], v[80:81], v[112:113], v[106:107]
	v_pk_fma_f32 v[106:107], v[74:75], v[122:123], v[100:101]
	v_mul_f32_e32 v101, 0x3d372713, v104
	v_mul_f32_e32 v100, 0x3fcc422a, v104
	v_fma_f32 v101, v104, v101, 1.0
	v_mul_f32_e32 v111, 0x3d372713, v106
	v_mul_f32_e32 v100, v100, v101
	v_mul_f32_e32 v101, 0x3fcc422a, v106
	v_fma_f32 v111, v106, v111, 1.0
	v_mul_f32_e32 v101, v101, v111
	v_mul_f32_e32 v101, 0xbfb8aa3b, v101
	v_exp_f32_e32 v101, v101
	v_lshlrev_b32_e32 v114, 16, v115
	v_and_b32_e32 v115, 0xffff0000, v115
	v_mul_f32_e32 v111, 0x3d372713, v105
	v_add_f32_e32 v101, 1.0, v101
	v_pk_fma_f32 v[102:103], v[76:77], v[114:115], v[102:103]
	v_rcp_f32_e32 v114, v101
	v_mul_f32_e32 v101, 0x3fcc422a, v105
	v_fma_f32 v111, v105, v111, 1.0
	v_mul_f32_e32 v101, v101, v111
	v_mul_f32_e32 v100, 0xbfb8aa3b, v100
	v_mul_f32_e32 v101, 0xbfb8aa3b, v101
	v_exp_f32_e32 v100, v100
	v_exp_f32_e32 v101, v101
	v_mul_f32_e32 v111, 0x3d372713, v113
	v_fma_f32 v111, v113, v111, 1.0
	v_add_f32_e32 v100, 1.0, v100
	v_add_f32_e32 v101, 1.0, v101
	v_rcp_f32_e32 v100, v100
	v_rcp_f32_e32 v101, v101
	s_nop 0
	v_pk_mul_f32 v[100:101], v[104:105], v[100:101]
	v_mul_f32_e32 v105, 0x3d372713, v107
	v_mul_f32_e32 v104, 0x3fcc422a, v107
	v_fma_f32 v105, v107, v105, 1.0
	v_mul_f32_e32 v104, v104, v105
	v_mul_f32_e32 v104, 0xbfb8aa3b, v104
	v_exp_f32_e32 v104, v104
	v_cvt_pk_bf16_f32 v100, v100, v101
	v_add_f32_e32 v104, 1.0, v104
	v_rcp_f32_e32 v115, v104
	s_nop 0
	v_pk_mul_f32 v[104:105], v[106:107], v[114:115]
	v_mul_f32_e32 v107, 0x3d372713, v112
	v_mul_f32_e32 v106, 0x3fcc422a, v112
	v_fma_f32 v107, v112, v107, 1.0
	v_mul_f32_e32 v106, v106, v107
	v_mul_f32_e32 v106, 0xbfb8aa3b, v106
	v_exp_f32_e32 v106, v106
	v_mul_f32_e32 v107, 0x3d372713, v102
	v_fma_f32 v107, v102, v107, 1.0
	v_add_f32_e32 v106, 1.0, v106
	v_rcp_f32_e32 v114, v106
	v_mul_f32_e32 v106, 0x3fcc422a, v102
	v_mul_f32_e32 v106, v106, v107
	v_mul_f32_e32 v107, 0x3fcc422a, v113
	v_mul_f32_e32 v107, v107, v111
	v_mul_f32_e32 v107, 0xbfb8aa3b, v107
	v_exp_f32_e32 v107, v107
	v_mul_f32_e32 v111, 0x3d372713, v103
	v_fma_f32 v111, v103, v111, 1.0
	v_mul_f32_e32 v106, 0xbfb8aa3b, v106
	v_add_f32_e32 v107, 1.0, v107
	v_rcp_f32_e32 v115, v107
	v_mul_f32_e32 v107, 0x3fcc422a, v103
	v_mul_f32_e32 v107, v107, v111
	v_mul_f32_e32 v107, 0xbfb8aa3b, v107
	v_exp_f32_e32 v106, v106
	v_exp_f32_e32 v107, v107
	v_or_b32_e32 v111, v110, v178
	v_pk_mul_f32 v[112:113], v[112:113], v[114:115]
	v_add_f32_e32 v106, 1.0, v106
	v_add_f32_e32 v107, 1.0, v107
	v_rcp_f32_e32 v106, v106
	v_rcp_f32_e32 v107, v107
	v_cvt_pk_bf16_f32 v101, v112, v113
	v_pk_mul_f32 v[106:107], v[102:103], v[106:107]
	v_cvt_pk_bf16_f32 v102, v104, v105
	v_lshlrev_b32_e32 v104, 10, v111
	v_mov_b32_e32 v105, v99
	v_lshl_add_u64 v[104:105], s[14:15], 0, v[104:105]
	v_lshl_add_u64 v[104:105], v[104:105], 0, s[12:13]
	v_cvt_pk_bf16_f32 v103, v106, v107
	v_lshl_add_u64 v[104:105], v[104:105], 0, v[164:165]
	global_store_dwordx4 v[104:105], v[100:103], off
	s_nop 1
	v_add_u32_e32 v100, 0x90, v179
	v_lshlrev_b32_e32 v101, 5, v100
	v_and_b32_e32 v102, 0x7be0, v101
	v_mad_i64_i32 v[100:101], s[2:3], v100, s10, v[170:171]
	v_lshl_add_u64 v[104:105], v[100:101], 0, v[98:99]
	v_lshl_add_u64 v[104:105], v[104:105], 0, v[164:165]
	s_waitcnt vmcnt(14)
	v_mov_b64_e32 v[104:105], v[200:201]
	v_mov_b64_e32 v[106:107], v[202:203]
	v_lshlrev_b32_e32 v112, 16, v104
	v_and_b32_e32 v113, 0xffff0000, v104
	v_lshlrev_b32_e32 v104, 16, v105
	v_and_b32_e32 v105, 0xffff0000, v105
	v_lshlrev_b32_e32 v114, 16, v106
	v_and_b32_e32 v115, 0xffff0000, v106
	v_pk_fma_f32 v[94:95], v[78:79], v[112:113], v[94:95]
	v_pk_fma_f32 v[104:105], v[80:81], v[104:105], v[96:97]
	v_pk_fma_f32 v[96:97], v[74:75], v[114:115], v[90:91]
	v_mul_f32_e32 v91, 0x3d372713, v94
	v_mul_f32_e32 v90, 0x3fcc422a, v94
	v_fma_f32 v91, v94, v91, 1.0
	v_mul_f32_e32 v103, 0x3d372713, v96
	v_mul_f32_e32 v90, v90, v91
	v_mul_f32_e32 v91, 0x3fcc422a, v96
	v_fma_f32 v103, v96, v103, 1.0
	v_mul_f32_e32 v91, v91, v103
	v_mul_f32_e32 v91, 0xbfb8aa3b, v91
	v_exp_f32_e32 v91, v91
	v_lshlrev_b32_e32 v106, 16, v107
	v_and_b32_e32 v107, 0xffff0000, v107
	v_mul_f32_e32 v103, 0x3d372713, v95
	v_add_f32_e32 v91, 1.0, v91
	v_pk_fma_f32 v[92:93], v[76:77], v[106:107], v[92:93]
	v_rcp_f32_e32 v106, v91
	v_mul_f32_e32 v91, 0x3fcc422a, v95
	v_fma_f32 v103, v95, v103, 1.0
	v_mul_f32_e32 v91, v91, v103
	v_mul_f32_e32 v90, 0xbfb8aa3b, v90
	v_mul_f32_e32 v91, 0xbfb8aa3b, v91
	v_exp_f32_e32 v90, v90
	v_exp_f32_e32 v91, v91
	v_mul_f32_e32 v103, 0x3d372713, v105
	v_fma_f32 v103, v105, v103, 1.0
	v_add_f32_e32 v90, 1.0, v90
	v_add_f32_e32 v91, 1.0, v91
	v_rcp_f32_e32 v90, v90
	v_rcp_f32_e32 v91, v91
	s_nop 0
	v_pk_mul_f32 v[90:91], v[94:95], v[90:91]
	v_mul_f32_e32 v95, 0x3d372713, v97
	v_mul_f32_e32 v94, 0x3fcc422a, v97
	v_fma_f32 v95, v97, v95, 1.0
	v_mul_f32_e32 v94, v94, v95
	v_mul_f32_e32 v94, 0xbfb8aa3b, v94
	v_exp_f32_e32 v94, v94
	v_cvt_pk_bf16_f32 v90, v90, v91
	v_add_f32_e32 v94, 1.0, v94
	v_rcp_f32_e32 v107, v94
	s_nop 0
	v_pk_mul_f32 v[94:95], v[96:97], v[106:107]
	v_mul_f32_e32 v97, 0x3d372713, v104
	v_mul_f32_e32 v96, 0x3fcc422a, v104
	v_fma_f32 v97, v104, v97, 1.0
	v_mul_f32_e32 v96, v96, v97
	v_mul_f32_e32 v96, 0xbfb8aa3b, v96
	v_exp_f32_e32 v96, v96
	v_mul_f32_e32 v97, 0x3d372713, v92
; __device__ __forceinline__ float fast_sigmoid(float v) { return __builtin_amdgcn_rcpf(1.0f + __builtin_amdgcn_exp2f(-v * LOG2E)); }
; __device__ __forceinline__ u32x4 pack8(f32x4 a, f32x4 b) { u32x4 w; w.x = cvt_pk_bf16(a[0], a[1]); w.y = cvt_pk_bf16(a[2], a[3]); w.z = cvt_pk_bf16(b[0], b[1]); w.w = cvt_pk_bf16(b[2], b[3]); return w; }
; __device__ __forceinline__ void unpack8(u32x4 w, f32x4& a, f32x4& b) { a = (f32x4){bf_lo(w.x), bf_hi(w.x), bf_lo(w.y), bf_hi(w.y)}; b = (f32x4){bf_lo(w.z), bf_hi(w.z), bf_lo(w.w), bf_hi(w.w)}; }
;     __device__ __forceinline__ void operator()(Acc& acc, const Unit& u, int wr, int wc, int fr, int fq) const {
;         const int R0 = u.pm * BM + wr * 64 + fr, gg = u.pm >> 2, nb = (u.pn & 1) * BM + wc * 64 + 8 * fq;
; #pragma unroll
;         for (int bj = 0; bj < 2; ++bj) { const int np = nb + bj * BJ, i = np >> 4, c0 = np & 15;
;             const f32x4 d0 = *(const f32x4*)(dskip + gg * 16 + c0), d1 = *(const f32x4*)(dskip + gg * 16 + c0 + 4);
; #pragma unroll
;             for (int ai = 0; ai < 2; ++ai)
; #pragma unroll
;                 for (int m = 0; m < 4; ++m) { const int R = R0 + ai * HALF + m * 16; const int token = (R & (ROWS_G - 1)) * TCH + i;
;                     f32x4 u0, u1; unpack8(*(const u32x4*)(a2 + (size_t)R * K2 + i * 16 + c0), u0, u1);
;                     f32x4 y0 = acc[ai][bj][m][0] + d0 * u0, y1 = acc[ai][bj][m][1] + d1 * u1;
; #pragma unroll
;                     for (int e = 0; e < 4; ++e) { { const float y = y0[e]; const float t = 1.5957691216057308f * y * (1.0f + 0.044715f * y * y); y0[e] = y * fast_sigmoid(t); }
;                                                   { const float y = y1[e]; const float t = 1.5957691216057308f * y * (1.0f + 0.044715f * y * y); y1[e] = y * fast_sigmoid(t); } }
;                     *(u32x4*)(gbuf + (size_t)token * 512 + gg * 16 + c0) = pack8(y0, y1); } }
;     }
	v_fma_f32 v97, v92, v97, 1.0
	v_add_f32_e32 v96, 1.0, v96
	v_rcp_f32_e32 v106, v96
	v_mul_f32_e32 v96, 0x3fcc422a, v92
	v_mul_f32_e32 v96, v96, v97
	v_mul_f32_e32 v97, 0x3fcc422a, v105
	v_mul_f32_e32 v97, v97, v103
	v_mul_f32_e32 v97, 0xbfb8aa3b, v97
	v_exp_f32_e32 v97, v97
	v_mul_f32_e32 v103, 0x3d372713, v93
	v_fma_f32 v103, v93, v103, 1.0
	v_mul_f32_e32 v96, 0xbfb8aa3b, v96
	v_add_f32_e32 v97, 1.0, v97
	v_rcp_f32_e32 v107, v97
	v_mul_f32_e32 v97, 0x3fcc422a, v93
	v_mul_f32_e32 v97, v97, v103
	v_mul_f32_e32 v97, 0xbfb8aa3b, v97
	v_exp_f32_e32 v96, v96
	v_exp_f32_e32 v97, v97
	v_or_b32_e32 v103, v102, v178
	v_pk_mul_f32 v[104:105], v[104:105], v[106:107]
	v_add_f32_e32 v96, 1.0, v96
	v_add_f32_e32 v97, 1.0, v97
	v_rcp_f32_e32 v96, v96
	v_rcp_f32_e32 v97, v97
	v_cvt_pk_bf16_f32 v91, v104, v105
	v_pk_mul_f32 v[96:97], v[92:93], v[96:97]
	v_cvt_pk_bf16_f32 v92, v94, v95
	v_lshlrev_b32_e32 v94, 10, v103
	v_mov_b32_e32 v95, v99
	v_lshl_add_u64 v[94:95], s[14:15], 0, v[94:95]
	v_lshl_add_u64 v[94:95], v[94:95], 0, s[12:13]
	v_cvt_pk_bf16_f32 v93, v96, v97
	v_lshl_add_u64 v[94:95], v[94:95], 0, v[164:165]
	global_store_dwordx4 v[94:95], v[90:93], off
	s_nop 1
	v_add_u32_e32 v90, 0xa0, v179
	v_lshlrev_b32_e32 v91, 5, v90
	v_and_b32_e32 v92, 0x7de0, v91
	v_mad_i64_i32 v[90:91], s[2:3], v90, s10, v[170:171]
	v_lshl_add_u64 v[94:95], v[90:91], 0, v[98:99]
	v_lshl_add_u64 v[94:95], v[94:95], 0, v[164:165]
	s_waitcnt vmcnt(14)
	v_mov_b64_e32 v[94:95], v[204:205]
	v_mov_b64_e32 v[96:97], v[206:207]
	v_lshlrev_b32_e32 v104, 16, v94
	v_and_b32_e32 v105, 0xffff0000, v94
	v_lshlrev_b32_e32 v94, 16, v95
	v_and_b32_e32 v95, 0xffff0000, v95
	v_lshlrev_b32_e32 v106, 16, v96
	v_and_b32_e32 v107, 0xffff0000, v96
	v_pk_fma_f32 v[86:87], v[78:79], v[104:105], v[86:87]
	v_pk_fma_f32 v[94:95], v[80:81], v[94:95], v[88:89]
	v_pk_fma_f32 v[88:89], v[74:75], v[106:107], v[82:83]
	v_mul_f32_e32 v83, 0x3d372713, v86
	v_mul_f32_e32 v82, 0x3fcc422a, v86
	v_fma_f32 v83, v86, v83, 1.0
	v_mul_f32_e32 v93, 0x3d372713, v88
	v_mul_f32_e32 v82, v82, v83
	v_mul_f32_e32 v83, 0x3fcc422a, v88
	v_fma_f32 v93, v88, v93, 1.0
	v_mul_f32_e32 v83, v83, v93
	v_mul_f32_e32 v83, 0xbfb8aa3b, v83
	v_exp_f32_e32 v83, v83
	v_lshlrev_b32_e32 v96, 16, v97
	v_and_b32_e32 v97, 0xffff0000, v97
	v_mul_f32_e32 v93, 0x3d372713, v87
	v_add_f32_e32 v83, 1.0, v83
	v_pk_fma_f32 v[84:85], v[76:77], v[96:97], v[84:85]
	v_rcp_f32_e32 v96, v83
	v_mul_f32_e32 v83, 0x3fcc422a, v87
	v_fma_f32 v93, v87, v93, 1.0
	v_mul_f32_e32 v83, v83, v93
	v_mul_f32_e32 v82, 0xbfb8aa3b, v82
	v_mul_f32_e32 v83, 0xbfb8aa3b, v83
	v_exp_f32_e32 v82, v82
	v_exp_f32_e32 v83, v83
	v_mul_f32_e32 v93, 0x3d372713, v95
	v_fma_f32 v93, v95, v93, 1.0
	v_add_f32_e32 v82, 1.0, v82
	v_add_f32_e32 v83, 1.0, v83
	v_rcp_f32_e32 v82, v82
	v_rcp_f32_e32 v83, v83
	s_nop 0
	v_pk_mul_f32 v[82:83], v[86:87], v[82:83]
	v_mul_f32_e32 v87, 0x3d372713, v89
	v_mul_f32_e32 v86, 0x3fcc422a, v89
	v_fma_f32 v87, v89, v87, 1.0
	v_mul_f32_e32 v86, v86, v87
	v_mul_f32_e32 v86, 0xbfb8aa3b, v86
	v_exp_f32_e32 v86, v86
	v_cvt_pk_bf16_f32 v82, v82, v83
	v_add_f32_e32 v86, 1.0, v86
	v_rcp_f32_e32 v97, v86
	s_nop 0
	v_pk_mul_f32 v[86:87], v[88:89], v[96:97]
	v_mul_f32_e32 v89, 0x3d372713, v94
	v_mul_f32_e32 v88, 0x3fcc422a, v94
	v_fma_f32 v89, v94, v89, 1.0
	v_mul_f32_e32 v88, v88, v89
	v_mul_f32_e32 v88, 0xbfb8aa3b, v88
	v_exp_f32_e32 v88, v88
	v_mul_f32_e32 v89, 0x3d372713, v84
	v_fma_f32 v89, v84, v89, 1.0
	v_add_f32_e32 v88, 1.0, v88
	v_rcp_f32_e32 v96, v88
	v_mul_f32_e32 v88, 0x3fcc422a, v84
	v_mul_f32_e32 v88, v88, v89
	v_mul_f32_e32 v89, 0x3fcc422a, v95
	v_mul_f32_e32 v89, v89, v93
	v_mul_f32_e32 v89, 0xbfb8aa3b, v89
	v_exp_f32_e32 v89, v89
	v_mul_f32_e32 v93, 0x3d372713, v85
	v_fma_f32 v93, v85, v93, 1.0
	v_mul_f32_e32 v88, 0xbfb8aa3b, v88
	v_add_f32_e32 v89, 1.0, v89
	v_rcp_f32_e32 v97, v89
	v_mul_f32_e32 v89, 0x3fcc422a, v85
	v_mul_f32_e32 v89, v89, v93
	v_mul_f32_e32 v89, 0xbfb8aa3b, v89
	v_exp_f32_e32 v88, v88
	v_exp_f32_e32 v89, v89
	v_or_b32_e32 v93, v92, v178
	v_pk_mul_f32 v[94:95], v[94:95], v[96:97]
	v_add_f32_e32 v88, 1.0, v88
	v_add_f32_e32 v89, 1.0, v89
	v_rcp_f32_e32 v88, v88
	v_rcp_f32_e32 v89, v89
	v_cvt_pk_bf16_f32 v83, v94, v95
	v_pk_mul_f32 v[88:89], v[84:85], v[88:89]
	v_cvt_pk_bf16_f32 v84, v86, v87
	v_lshlrev_b32_e32 v86, 10, v93
	v_mov_b32_e32 v87, v99
	v_lshl_add_u64 v[86:87], s[14:15], 0, v[86:87]
	v_lshl_add_u64 v[86:87], v[86:87], 0, s[12:13]
	v_cvt_pk_bf16_f32 v85, v88, v89
	v_lshl_add_u64 v[86:87], v[86:87], 0, v[164:165]
	global_store_dwordx4 v[86:87], v[82:85], off
	s_nop 1
	v_add_u32_e32 v82, 0xb0, v179
	v_lshlrev_b32_e32 v83, 5, v82
	v_and_b32_e32 v84, 0x7fe0, v83
	v_mad_i64_i32 v[82:83], s[2:3], v82, s10, v[170:171]
	v_lshl_add_u64 v[86:87], v[82:83], 0, v[98:99]
	v_lshl_add_u64 v[86:87], v[86:87], 0, v[164:165]
	s_waitcnt vmcnt(14)
; __device__ __forceinline__ float fast_sigmoid(float v) { return __builtin_amdgcn_rcpf(1.0f + __builtin_amdgcn_exp2f(-v * LOG2E)); }
; __device__ __forceinline__ u32x4 pack8(f32x4 a, f32x4 b) { u32x4 w; w.x = cvt_pk_bf16(a[0], a[1]); w.y = cvt_pk_bf16(a[2], a[3]); w.z = cvt_pk_bf16(b[0], b[1]); w.w = cvt_pk_bf16(b[2], b[3]); return w; }
; __device__ __forceinline__ void unpack8(u32x4 w, f32x4& a, f32x4& b) { a = (f32x4){bf_lo(w.x), bf_hi(w.x), bf_lo(w.y), bf_hi(w.y)}; b = (f32x4){bf_lo(w.z), bf_hi(w.z), bf_lo(w.w), bf_hi(w.w)}; }
;     __device__ __forceinline__ void operator()(Acc& acc, const Unit& u, int wr, int wc, int fr, int fq) const {
;         const int R0 = u.pm * BM + wr * 64 + fr, gg = u.pm >> 2, nb = (u.pn & 1) * BM + wc * 64 + 8 * fq;
; #pragma unroll
;         for (int bj = 0; bj < 2; ++bj) { const int np = nb + bj * BJ, i = np >> 4, c0 = np & 15;
;             const f32x4 d0 = *(const f32x4*)(dskip + gg * 16 + c0), d1 = *(const f32x4*)(dskip + gg * 16 + c0 + 4);
; #pragma unroll
;             for (int ai = 0; ai < 2; ++ai)
; #pragma unroll
;                 for (int m = 0; m < 4; ++m) { const int R = R0 + ai * HALF + m * 16; const int token = (R & (ROWS_G - 1)) * TCH + i;
;                     f32x4 u0, u1; unpack8(*(const u32x4*)(a2 + (size_t)R * K2 + i * 16 + c0), u0, u1);
;                     f32x4 y0 = acc[ai][bj][m][0] + d0 * u0, y1 = acc[ai][bj][m][1] + d1 * u1;
; #pragma unroll
;                     for (int e = 0; e < 4; ++e) { { const float y = y0[e]; const float t = 1.5957691216057308f * y * (1.0f + 0.044715f * y * y); y0[e] = y * fast_sigmoid(t); }
;                                                   { const float y = y1[e]; const float t = 1.5957691216057308f * y * (1.0f + 0.044715f * y * y); y1[e] = y * fast_sigmoid(t); } }
;                     *(u32x4*)(gbuf + (size_t)token * 512 + gg * 16 + c0) = pack8(y0, y1); } }
;     }
	v_mov_b64_e32 v[86:87], v[208:209]
	v_mov_b64_e32 v[88:89], v[210:211]
	s_movk_i32 s2, 0x1f0
	v_lshlrev_b32_e32 v94, 16, v86
	v_and_b32_e32 v95, 0xffff0000, v86
	v_lshlrev_b32_e32 v86, 16, v87
	v_and_b32_e32 v87, 0xffff0000, v87
	v_lshlrev_b32_e32 v96, 16, v88
	v_and_b32_e32 v97, 0xffff0000, v88
	v_pk_fma_f32 v[62:63], v[78:79], v[94:95], v[62:63]
	v_pk_fma_f32 v[80:81], v[80:81], v[86:87], v[64:65]
	v_pk_fma_f32 v[64:65], v[74:75], v[96:97], v[58:59]
	v_mul_f32_e32 v59, 0x3d372713, v62
	v_mul_f32_e32 v58, 0x3fcc422a, v62
	v_fma_f32 v59, v62, v59, 1.0
	v_mul_f32_e32 v74, 0x3d372713, v64
	v_mul_f32_e32 v58, v58, v59
	v_mul_f32_e32 v59, 0x3fcc422a, v64
	v_fma_f32 v74, v64, v74, 1.0
	v_mul_f32_e32 v59, v59, v74
	v_mul_f32_e32 v59, 0xbfb8aa3b, v59
	v_exp_f32_e32 v59, v59
	v_mul_f32_e32 v75, 0x3d372713, v63
	v_fma_f32 v75, v63, v75, 1.0
	v_mul_f32_e32 v58, 0xbfb8aa3b, v58
	v_add_f32_e32 v59, 1.0, v59
	v_rcp_f32_e32 v74, v59
	v_mul_f32_e32 v59, 0x3fcc422a, v63
	v_mul_f32_e32 v59, v59, v75
	v_mul_f32_e32 v59, 0xbfb8aa3b, v59
	v_exp_f32_e32 v58, v58
	v_exp_f32_e32 v59, v59
	v_lshlrev_b32_e32 v88, 16, v89
	v_and_b32_e32 v89, 0xffff0000, v89
	v_add_f32_e32 v58, 1.0, v58
	v_add_f32_e32 v59, 1.0, v59
	v_rcp_f32_e32 v58, v58
	v_rcp_f32_e32 v59, v59
	v_pk_fma_f32 v[60:61], v[76:77], v[88:89], v[60:61]
	v_pk_mul_f32 v[58:59], v[62:63], v[58:59]
	v_mul_f32_e32 v63, 0x3d372713, v65
	v_mul_f32_e32 v62, 0x3fcc422a, v65
	v_fma_f32 v63, v65, v63, 1.0
	v_mul_f32_e32 v62, v62, v63
	v_mul_f32_e32 v62, 0xbfb8aa3b, v62
	v_exp_f32_e32 v62, v62
	v_mul_f32_e32 v76, 0x3d372713, v61
	v_fma_f32 v76, v61, v76, 1.0
	v_cvt_pk_bf16_f32 v58, v58, v59
	v_add_f32_e32 v62, 1.0, v62
	v_rcp_f32_e32 v75, v62
	s_nop 0
	v_pk_mul_f32 v[62:63], v[64:65], v[74:75]
	v_mul_f32_e32 v65, 0x3d372713, v80
	v_mul_f32_e32 v64, 0x3fcc422a, v80
	v_fma_f32 v65, v80, v65, 1.0
	v_mul_f32_e32 v64, v64, v65
	v_mul_f32_e32 v64, 0xbfb8aa3b, v64
	v_exp_f32_e32 v64, v64
	v_mul_f32_e32 v65, 0x3d372713, v60
	v_fma_f32 v65, v60, v65, 1.0
	v_mul_f32_e32 v75, 0x3d372713, v81
	v_add_f32_e32 v64, 1.0, v64
	v_rcp_f32_e32 v74, v64
	v_mul_f32_e32 v64, 0x3fcc422a, v60
	v_mul_f32_e32 v64, v64, v65
	v_mul_f32_e32 v65, 0x3fcc422a, v81
	v_fma_f32 v75, v81, v75, 1.0
	v_mul_f32_e32 v65, v65, v75
	v_mul_f32_e32 v65, 0xbfb8aa3b, v65
	v_exp_f32_e32 v65, v65
	v_mul_f32_e32 v64, 0xbfb8aa3b, v64
	v_exp_f32_e32 v64, v64
	v_add_f32_e32 v65, 1.0, v65
	v_rcp_f32_e32 v75, v65
	v_mul_f32_e32 v65, 0x3fcc422a, v61
	v_mul_f32_e32 v65, v65, v76
	v_mul_f32_e32 v65, 0xbfb8aa3b, v65
	v_exp_f32_e32 v65, v65
	v_add_f32_e32 v64, 1.0, v64
	v_rcp_f32_e32 v64, v64
	v_or_b32_e32 v76, v84, v178
	v_add_f32_e32 v65, 1.0, v65
	v_rcp_f32_e32 v65, v65
	v_pk_mul_f32 v[74:75], v[80:81], v[74:75]
	v_lshlrev_b32_e32 v98, 10, v76
	v_cvt_pk_bf16_f32 v59, v74, v75
	v_pk_mul_f32 v[64:65], v[60:61], v[64:65]
	v_cvt_pk_bf16_f32 v60, v62, v63
	v_lshl_add_u64 v[62:63], s[14:15], 0, v[98:99]
	v_bitop3_b32 v75, v177, s2, 32 bitop3:0xc8
	v_lshl_add_u64 v[62:63], v[62:63], 0, s[12:13]
	v_lshlrev_b32_e32 v98, 1, v75
	v_cvt_pk_bf16_f32 v61, v64, v65
	v_lshl_add_u64 v[62:63], v[62:63], 0, v[164:165]
	v_lshl_add_u64 v[76:77], v[168:169], 0, v[98:99]
	global_store_dwordx4 v[62:63], v[58:61], off
	v_lshl_add_u64 v[76:77], v[76:77], 0, v[164:165]
	s_mov_b64 s[2:3], -1
	v_or_b32_e32 v58, 32, v177
	v_lshrrev_b32_e32 v74, 4, v58
	global_load_dwordx4 v[58:61], v[166:167], off offset:16
	global_load_dwordx4 v[62:65], v[166:167], off
	s_nop 0
	global_load_dwordx4 v[76:79], v[76:77], off
	s_waitcnt vmcnt(0)
	v_lshlrev_b32_e32 v80, 16, v76
	v_and_b32_e32 v81, 0xffff0000, v76
	v_lshlrev_b32_e32 v76, 16, v77
	v_and_b32_e32 v77, 0xffff0000, v77
	v_lshlrev_b32_e32 v86, 16, v78
	v_and_b32_e32 v87, 0xffff0000, v78
	v_pk_fma_f32 v[70:71], v[62:63], v[80:81], v[70:71]
	v_pk_fma_f32 v[72:73], v[64:65], v[76:77], v[72:73]
	v_pk_fma_f32 v[76:77], v[58:59], v[86:87], v[66:67]
	v_mul_f32_e32 v67, 0x3d372713, v70
	v_mul_f32_e32 v66, 0x3fcc422a, v70
	v_fma_f32 v67, v70, v67, 1.0
	v_mul_f32_e32 v75, 0x3d372713, v76
	v_mul_f32_e32 v66, v66, v67
	v_mul_f32_e32 v67, 0x3fcc422a, v76
	v_fma_f32 v75, v76, v75, 1.0
	v_mul_f32_e32 v67, v67, v75
	v_mul_f32_e32 v67, 0xbfb8aa3b, v67
	v_exp_f32_e32 v67, v67
	v_lshlrev_b32_e32 v78, 16, v79
	v_and_b32_e32 v79, 0xffff0000, v79
	v_mul_f32_e32 v75, 0x3d372713, v71
	v_add_f32_e32 v67, 1.0, v67
	v_pk_fma_f32 v[68:69], v[60:61], v[78:79], v[68:69]
	v_rcp_f32_e32 v78, v67
	v_mul_f32_e32 v67, 0x3fcc422a, v71
	v_fma_f32 v75, v71, v75, 1.0
	v_mul_f32_e32 v67, v67, v75
	v_mul_f32_e32 v66, 0xbfb8aa3b, v66
	v_mul_f32_e32 v67, 0xbfb8aa3b, v67
	v_exp_f32_e32 v66, v66
	v_exp_f32_e32 v67, v67
	v_mul_f32_e32 v75, 0x3fcc422a, v72
	v_add_f32_e32 v66, 1.0, v66
	v_add_f32_e32 v67, 1.0, v67
	v_rcp_f32_e32 v66, v66
	v_rcp_f32_e32 v67, v67
	s_nop 0
	v_pk_mul_f32 v[66:67], v[70:71], v[66:67]
	v_mul_f32_e32 v71, 0x3d372713, v77
	v_mul_f32_e32 v70, 0x3fcc422a, v77
	v_fma_f32 v71, v77, v71, 1.0
	v_mul_f32_e32 v70, v70, v71
	v_mul_f32_e32 v70, 0xbfb8aa3b, v70
	v_exp_f32_e32 v70, v70
	v_cvt_pk_bf16_f32 v66, v66, v67
	v_add_f32_e32 v70, 1.0, v70
	v_rcp_f32_e32 v79, v70
	s_nop 0
	v_pk_mul_f32 v[70:71], v[76:77], v[78:79]
	v_mul_f32_e32 v76, 0x3d372713, v72
	v_fma_f32 v76, v72, v76, 1.0
	v_mul_f32_e32 v75, v75, v76
	v_mul_f32_e32 v75, 0xbfb8aa3b, v75
	v_exp_f32_e32 v75, v75
	v_mul_f32_e32 v77, 0x3d372713, v68
	v_fma_f32 v77, v68, v77, 1.0
	v_add_f32_e32 v75, 1.0, v75
	v_rcp_f32_e32 v76, v75
	v_mul_f32_e32 v75, 0x3fcc422a, v68
	v_mul_f32_e32 v75, v75, v77
	v_mul_f32_e32 v75, 0xbfb8aa3b, v75
	v_exp_f32_e32 v75, v75
	v_mul_f32_e32 v77, 0x3d372713, v73
	v_fma_f32 v77, v73, v77, 1.0
; __device__ __forceinline__ float fast_sigmoid(float v) { return __builtin_amdgcn_rcpf(1.0f + __builtin_amdgcn_exp2f(-v * LOG2E)); }
; __device__ __forceinline__ u32x4 pack8(f32x4 a, f32x4 b) { u32x4 w; w.x = cvt_pk_bf16(a[0], a[1]); w.y = cvt_pk_bf16(a[2], a[3]); w.z = cvt_pk_bf16(b[0], b[1]); w.w = cvt_pk_bf16(b[2], b[3]); return w; }
; __device__ __forceinline__ void unpack8(u32x4 w, f32x4& a, f32x4& b) { a = (f32x4){bf_lo(w.x), bf_hi(w.x), bf_lo(w.y), bf_hi(w.y)}; b = (f32x4){bf_lo(w.z), bf_hi(w.z), bf_lo(w.w), bf_hi(w.w)}; }
;     __device__ __forceinline__ void operator()(Acc& acc, const Unit& u, int wr, int wc, int fr, int fq) const {
;         const int R0 = u.pm * BM + wr * 64 + fr, gg = u.pm >> 2, nb = (u.pn & 1) * BM + wc * 64 + 8 * fq;
; #pragma unroll
;         for (int bj = 0; bj < 2; ++bj) { const int np = nb + bj * BJ, i = np >> 4, c0 = np & 15;
;             const f32x4 d0 = *(const f32x4*)(dskip + gg * 16 + c0), d1 = *(const f32x4*)(dskip + gg * 16 + c0 + 4);
; #pragma unroll
;             for (int ai = 0; ai < 2; ++ai)
; #pragma unroll
;                 for (int m = 0; m < 4; ++m) { const int R = R0 + ai * HALF + m * 16; const int token = (R & (ROWS_G - 1)) * TCH + i;
;                     f32x4 u0, u1; unpack8(*(const u32x4*)(a2 + (size_t)R * K2 + i * 16 + c0), u0, u1);
;                     f32x4 y0 = acc[ai][bj][m][0] + d0 * u0, y1 = acc[ai][bj][m][1] + d1 * u1;
; #pragma unroll
;                     for (int e = 0; e < 4; ++e) { { const float y = y0[e]; const float t = 1.5957691216057308f * y * (1.0f + 0.044715f * y * y); y0[e] = y * fast_sigmoid(t); }
;                                                   { const float y = y1[e]; const float t = 1.5957691216057308f * y * (1.0f + 0.044715f * y * y); y1[e] = y * fast_sigmoid(t); } }
;                     *(u32x4*)(gbuf + (size_t)token * 512 + gg * 16 + c0) = pack8(y0, y1); } }
;     }
	v_add_f32_e32 v75, 1.0, v75
	v_rcp_f32_e32 v78, v75
	v_mul_f32_e32 v75, 0x3fcc422a, v73
	v_mul_f32_e32 v75, v75, v77
	v_mul_f32_e32 v75, 0xbfb8aa3b, v75
	v_exp_f32_e32 v75, v75
	s_nop 0
	v_add_f32_e32 v75, 1.0, v75
	v_rcp_f32_e32 v77, v75
	v_mul_f32_e32 v75, 0x3fcc422a, v69
	v_pk_mul_f32 v[72:73], v[72:73], v[76:77]
	v_mul_f32_e32 v76, 0x3d372713, v69
	v_fma_f32 v76, v69, v76, 1.0
	v_mul_f32_e32 v75, v75, v76
	v_mul_f32_e32 v75, 0xbfb8aa3b, v75
	v_exp_f32_e32 v75, v75
	v_cvt_pk_bf16_f32 v67, v72, v73
	v_add_f32_e32 v75, 1.0, v75
	v_rcp_f32_e32 v79, v75
	v_or_b32_e32 v75, v74, v176
	v_pk_mul_f32 v[76:77], v[68:69], v[78:79]
	v_cvt_pk_bf16_f32 v68, v70, v71
	v_lshlrev_b32_e32 v70, 10, v75
	v_mov_b32_e32 v71, v99
	v_lshl_add_u64 v[70:71], s[14:15], 0, v[70:71]
	v_lshl_add_u64 v[70:71], v[70:71], 0, s[12:13]
	v_cvt_pk_bf16_f32 v69, v76, v77
	v_lshl_add_u64 v[70:71], v[70:71], 0, v[164:165]
	global_store_dwordx4 v[70:71], v[66:69], off
	s_nop 1
	v_lshl_add_u64 v[66:67], v[132:133], 0, v[98:99]
	v_lshl_add_u64 v[66:67], v[66:67], 0, v[164:165]
	v_mov_b64_e32 v[66:67], v[220:221]
	v_mov_b64_e32 v[68:69], v[222:223]
	v_lshlrev_b32_e32 v70, 16, v66
	v_and_b32_e32 v71, 0xffff0000, v66
	v_lshlrev_b32_e32 v66, 16, v67
	v_and_b32_e32 v67, 0xffff0000, v67
	v_lshlrev_b32_e32 v72, 16, v68
	v_and_b32_e32 v73, 0xffff0000, v68
	v_pk_fma_f32 v[54:55], v[62:63], v[70:71], v[54:55]
	v_lshlrev_b32_e32 v68, 16, v69
	v_and_b32_e32 v69, 0xffff0000, v69
	v_pk_fma_f32 v[66:67], v[64:65], v[66:67], v[56:57]
	v_pk_fma_f32 v[56:57], v[58:59], v[72:73], v[50:51]
	v_mul_f32_e32 v51, 0x3d372713, v54
	v_pk_fma_f32 v[52:53], v[60:61], v[68:69], v[52:53]
	v_mul_f32_e32 v50, 0x3fcc422a, v54
	v_fma_f32 v51, v54, v51, 1.0
	v_mul_f32_e32 v68, 0x3d372713, v56
	v_mul_f32_e32 v50, v50, v51
	v_mul_f32_e32 v51, 0x3fcc422a, v56
	v_fma_f32 v68, v56, v68, 1.0
	v_mul_f32_e32 v51, v51, v68
	v_mul_f32_e32 v51, 0xbfb8aa3b, v51
	v_exp_f32_e32 v51, v51
	v_mul_f32_e32 v69, 0x3d372713, v55
	v_fma_f32 v69, v55, v69, 1.0
	v_mul_f32_e32 v50, 0xbfb8aa3b, v50
	v_add_f32_e32 v51, 1.0, v51
	v_rcp_f32_e32 v68, v51
	v_mul_f32_e32 v51, 0x3fcc422a, v55
	v_mul_f32_e32 v51, v51, v69
	v_mul_f32_e32 v51, 0xbfb8aa3b, v51
	v_exp_f32_e32 v50, v50
	v_exp_f32_e32 v51, v51
	v_add_f32_e32 v50, 1.0, v50
	v_add_f32_e32 v51, 1.0, v51
	v_rcp_f32_e32 v50, v50
	v_rcp_f32_e32 v51, v51
	s_nop 0
	v_pk_mul_f32 v[50:51], v[54:55], v[50:51]
	v_mul_f32_e32 v55, 0x3d372713, v57
	v_mul_f32_e32 v54, 0x3fcc422a, v57
	v_fma_f32 v55, v57, v55, 1.0
	v_mul_f32_e32 v54, v54, v55
	v_mul_f32_e32 v54, 0xbfb8aa3b, v54
	v_exp_f32_e32 v54, v54
	v_cvt_pk_bf16_f32 v50, v50, v51
	v_add_f32_e32 v54, 1.0, v54
	v_rcp_f32_e32 v69, v54
	s_nop 0
	v_pk_mul_f32 v[54:55], v[56:57], v[68:69]
	v_mul_f32_e32 v57, 0x3d372713, v66
	v_mul_f32_e32 v56, 0x3fcc422a, v66
	v_fma_f32 v57, v66, v57, 1.0
	v_mul_f32_e32 v56, v56, v57
	v_mul_f32_e32 v56, 0xbfb8aa3b, v56
	v_exp_f32_e32 v56, v56
	v_mul_f32_e32 v57, 0x3d372713, v52
	v_fma_f32 v57, v52, v57, 1.0
	v_mul_f32_e32 v69, 0x3d372713, v67
	v_add_f32_e32 v56, 1.0, v56
	v_rcp_f32_e32 v68, v56
	v_mul_f32_e32 v56, 0x3fcc422a, v52
	v_mul_f32_e32 v56, v56, v57
	v_mul_f32_e32 v57, 0x3fcc422a, v67
	v_fma_f32 v69, v67, v69, 1.0
	v_mul_f32_e32 v57, v57, v69
	v_mul_f32_e32 v57, 0xbfb8aa3b, v57
	v_exp_f32_e32 v57, v57
	v_mul_f32_e32 v56, 0xbfb8aa3b, v56
	v_exp_f32_e32 v56, v56
	v_add_f32_e32 v57, 1.0, v57
	v_rcp_f32_e32 v69, v57
	v_mul_f32_e32 v57, 0x3fcc422a, v53
	v_add_f32_e32 v56, 1.0, v56
	v_rcp_f32_e32 v56, v56
	v_pk_mul_f32 v[66:67], v[66:67], v[68:69]
	v_mul_f32_e32 v68, 0x3d372713, v53
	v_fma_f32 v68, v53, v68, 1.0
	v_mul_f32_e32 v57, v57, v68
	v_mul_f32_e32 v57, 0xbfb8aa3b, v57
	v_exp_f32_e32 v57, v57
	v_or_b32_e32 v68, v134, v74
	v_cvt_pk_bf16_f32 v51, v66, v67
	v_add_f32_e32 v57, 1.0, v57
	v_rcp_f32_e32 v57, v57
	s_nop 0
	v_pk_mul_f32 v[56:57], v[52:53], v[56:57]
	v_cvt_pk_bf16_f32 v52, v54, v55
	v_lshlrev_b32_e32 v54, 10, v68
	v_mov_b32_e32 v55, v99
	v_lshl_add_u64 v[54:55], s[14:15], 0, v[54:55]
	v_lshl_add_u64 v[54:55], v[54:55], 0, s[12:13]
	v_cvt_pk_bf16_f32 v53, v56, v57
	v_lshl_add_u64 v[54:55], v[54:55], 0, v[164:165]
	global_store_dwordx4 v[54:55], v[50:53], off
	s_nop 1
	v_lshl_add_u64 v[50:51], v[124:125], 0, v[98:99]
	v_lshl_add_u64 v[50:51], v[50:51], 0, v[164:165]
	v_mov_b64_e32 v[50:51], v[224:225]
	v_mov_b64_e32 v[52:53], v[226:227]
	v_lshlrev_b32_e32 v54, 16, v50
	v_and_b32_e32 v55, 0xffff0000, v50
	v_lshlrev_b32_e32 v50, 16, v51
	v_and_b32_e32 v51, 0xffff0000, v51
	v_lshlrev_b32_e32 v56, 16, v52
	v_and_b32_e32 v57, 0xffff0000, v52
	v_pk_fma_f32 v[46:47], v[62:63], v[54:55], v[46:47]
	v_lshlrev_b32_e32 v52, 16, v53
	v_and_b32_e32 v53, 0xffff0000, v53
	v_pk_fma_f32 v[50:51], v[64:65], v[50:51], v[48:49]
	v_pk_fma_f32 v[48:49], v[58:59], v[56:57], v[42:43]
	v_mul_f32_e32 v43, 0x3d372713, v46
	v_pk_fma_f32 v[44:45], v[60:61], v[52:53], v[44:45]
	v_mul_f32_e32 v42, 0x3fcc422a, v46
	v_fma_f32 v43, v46, v43, 1.0
	v_mul_f32_e32 v52, 0x3d372713, v48
	v_mul_f32_e32 v42, v42, v43
	v_mul_f32_e32 v43, 0x3fcc422a, v48
	v_fma_f32 v52, v48, v52, 1.0
	v_mul_f32_e32 v43, v43, v52
	v_mul_f32_e32 v43, 0xbfb8aa3b, v43
	v_exp_f32_e32 v43, v43
	v_mul_f32_e32 v53, 0x3d372713, v47
	v_fma_f32 v53, v47, v53, 1.0
	v_mul_f32_e32 v42, 0xbfb8aa3b, v42
	v_add_f32_e32 v43, 1.0, v43
	v_rcp_f32_e32 v52, v43
	v_mul_f32_e32 v43, 0x3fcc422a, v47
	v_mul_f32_e32 v43, v43, v53
	v_mul_f32_e32 v43, 0xbfb8aa3b, v43
	v_exp_f32_e32 v42, v42
	v_exp_f32_e32 v43, v43
	v_add_f32_e32 v42, 1.0, v42
	v_add_f32_e32 v43, 1.0, v43
	v_rcp_f32_e32 v42, v42
	v_rcp_f32_e32 v43, v43
	s_nop 0
	v_pk_mul_f32 v[42:43], v[46:47], v[42:43]
	v_mul_f32_e32 v47, 0x3d372713, v49
; __device__ __forceinline__ float fast_sigmoid(float v) { return __builtin_amdgcn_rcpf(1.0f + __builtin_amdgcn_exp2f(-v * LOG2E)); }
; __device__ __forceinline__ u32x4 pack8(f32x4 a, f32x4 b) { u32x4 w; w.x = cvt_pk_bf16(a[0], a[1]); w.y = cvt_pk_bf16(a[2], a[3]); w.z = cvt_pk_bf16(b[0], b[1]); w.w = cvt_pk_bf16(b[2], b[3]); return w; }
; __device__ __forceinline__ void unpack8(u32x4 w, f32x4& a, f32x4& b) { a = (f32x4){bf_lo(w.x), bf_hi(w.x), bf_lo(w.y), bf_hi(w.y)}; b = (f32x4){bf_lo(w.z), bf_hi(w.z), bf_lo(w.w), bf_hi(w.w)}; }
;     __device__ __forceinline__ void operator()(Acc& acc, const Unit& u, int wr, int wc, int fr, int fq) const {
;         const int R0 = u.pm * BM + wr * 64 + fr, gg = u.pm >> 2, nb = (u.pn & 1) * BM + wc * 64 + 8 * fq;
; #pragma unroll
;         for (int bj = 0; bj < 2; ++bj) { const int np = nb + bj * BJ, i = np >> 4, c0 = np & 15;
;             const f32x4 d0 = *(const f32x4*)(dskip + gg * 16 + c0), d1 = *(const f32x4*)(dskip + gg * 16 + c0 + 4);
; #pragma unroll
;             for (int ai = 0; ai < 2; ++ai)
; #pragma unroll
;                 for (int m = 0; m < 4; ++m) { const int R = R0 + ai * HALF + m * 16; const int token = (R & (ROWS_G - 1)) * TCH + i;
;                     f32x4 u0, u1; unpack8(*(const u32x4*)(a2 + (size_t)R * K2 + i * 16 + c0), u0, u1);
;                     f32x4 y0 = acc[ai][bj][m][0] + d0 * u0, y1 = acc[ai][bj][m][1] + d1 * u1;
; #pragma unroll
;                     for (int e = 0; e < 4; ++e) { { const float y = y0[e]; const float t = 1.5957691216057308f * y * (1.0f + 0.044715f * y * y); y0[e] = y * fast_sigmoid(t); }
;                                                   { const float y = y1[e]; const float t = 1.5957691216057308f * y * (1.0f + 0.044715f * y * y); y1[e] = y * fast_sigmoid(t); } }
;                     *(u32x4*)(gbuf + (size_t)token * 512 + gg * 16 + c0) = pack8(y0, y1); } }
;     }
	v_mul_f32_e32 v46, 0x3fcc422a, v49
	v_fma_f32 v47, v49, v47, 1.0
	v_mul_f32_e32 v46, v46, v47
	v_mul_f32_e32 v46, 0xbfb8aa3b, v46
	v_exp_f32_e32 v46, v46
	v_cvt_pk_bf16_f32 v42, v42, v43
	v_add_f32_e32 v46, 1.0, v46
	v_rcp_f32_e32 v53, v46
	s_nop 0
	v_pk_mul_f32 v[46:47], v[48:49], v[52:53]
	v_mul_f32_e32 v49, 0x3d372713, v50
	v_mul_f32_e32 v48, 0x3fcc422a, v50
	v_fma_f32 v49, v50, v49, 1.0
	v_mul_f32_e32 v48, v48, v49
	v_mul_f32_e32 v48, 0xbfb8aa3b, v48
	v_exp_f32_e32 v48, v48
	v_mul_f32_e32 v49, 0x3d372713, v44
	v_fma_f32 v49, v44, v49, 1.0
	v_mul_f32_e32 v53, 0x3d372713, v51
	v_add_f32_e32 v48, 1.0, v48
	v_rcp_f32_e32 v52, v48
	v_mul_f32_e32 v48, 0x3fcc422a, v44
	v_mul_f32_e32 v48, v48, v49
	v_mul_f32_e32 v49, 0x3fcc422a, v51
	v_fma_f32 v53, v51, v53, 1.0
	v_mul_f32_e32 v49, v49, v53
	v_mul_f32_e32 v49, 0xbfb8aa3b, v49
	v_exp_f32_e32 v49, v49
	v_mul_f32_e32 v48, 0xbfb8aa3b, v48
	v_exp_f32_e32 v48, v48
	v_add_f32_e32 v49, 1.0, v49
	v_rcp_f32_e32 v53, v49
	v_mul_f32_e32 v49, 0x3fcc422a, v45
	v_add_f32_e32 v48, 1.0, v48
	v_rcp_f32_e32 v48, v48
	v_pk_mul_f32 v[50:51], v[50:51], v[52:53]
	v_mul_f32_e32 v52, 0x3d372713, v45
	v_fma_f32 v52, v45, v52, 1.0
	v_mul_f32_e32 v49, v49, v52
	v_mul_f32_e32 v49, 0xbfb8aa3b, v49
	v_exp_f32_e32 v49, v49
	v_or_b32_e32 v52, v126, v74
	v_cvt_pk_bf16_f32 v43, v50, v51
	v_add_f32_e32 v49, 1.0, v49
	v_rcp_f32_e32 v49, v49
	s_nop 0
	v_pk_mul_f32 v[48:49], v[44:45], v[48:49]
	v_cvt_pk_bf16_f32 v44, v46, v47
	v_lshlrev_b32_e32 v46, 10, v52
	v_mov_b32_e32 v47, v99
	v_lshl_add_u64 v[46:47], s[14:15], 0, v[46:47]
	v_lshl_add_u64 v[46:47], v[46:47], 0, s[12:13]
	v_cvt_pk_bf16_f32 v45, v48, v49
	v_lshl_add_u64 v[46:47], v[46:47], 0, v[164:165]
	global_store_dwordx4 v[46:47], v[42:45], off
	s_nop 1
	v_lshl_add_u64 v[42:43], v[116:117], 0, v[98:99]
	v_lshl_add_u64 v[42:43], v[42:43], 0, v[164:165]
	v_mov_b64_e32 v[42:43], v[228:229]
	v_mov_b64_e32 v[44:45], v[230:231]
	v_lshlrev_b32_e32 v46, 16, v42
	v_and_b32_e32 v47, 0xffff0000, v42
	v_lshlrev_b32_e32 v42, 16, v43
	v_and_b32_e32 v43, 0xffff0000, v43
	v_lshlrev_b32_e32 v48, 16, v44
	v_and_b32_e32 v49, 0xffff0000, v44
	v_lshlrev_b32_e32 v44, 16, v45
	v_and_b32_e32 v45, 0xffff0000, v45
	v_pk_fma_f32 v[38:39], v[62:63], v[46:47], v[38:39]
	v_pk_fma_f32 v[40:41], v[64:65], v[42:43], v[40:41]
	v_pk_fma_f32 v[42:43], v[60:61], v[44:45], v[36:37]
	v_pk_fma_f32 v[36:37], v[58:59], v[48:49], v[34:35]
	v_mul_f32_e32 v35, 0x3d372713, v38
	v_mul_f32_e32 v34, 0x3fcc422a, v38
	v_fma_f32 v35, v38, v35, 1.0
	v_mul_f32_e32 v44, 0x3d372713, v36
	v_mul_f32_e32 v34, v34, v35
	v_mul_f32_e32 v35, 0x3fcc422a, v36
	v_fma_f32 v44, v36, v44, 1.0
	v_mul_f32_e32 v35, v35, v44
	v_mul_f32_e32 v35, 0xbfb8aa3b, v35
	v_exp_f32_e32 v35, v35
	v_mul_f32_e32 v45, 0x3d372713, v39
	v_fma_f32 v45, v39, v45, 1.0
	v_mul_f32_e32 v34, 0xbfb8aa3b, v34
	v_add_f32_e32 v35, 1.0, v35
	v_rcp_f32_e32 v44, v35
	v_mul_f32_e32 v35, 0x3fcc422a, v39
	v_mul_f32_e32 v35, v35, v45
	v_mul_f32_e32 v35, 0xbfb8aa3b, v35
	v_exp_f32_e32 v34, v34
	v_exp_f32_e32 v35, v35
	v_add_f32_e32 v34, 1.0, v34
	v_add_f32_e32 v35, 1.0, v35
	v_rcp_f32_e32 v34, v34
	v_rcp_f32_e32 v35, v35
	s_nop 0
	v_pk_mul_f32 v[34:35], v[38:39], v[34:35]
	v_mul_f32_e32 v39, 0x3d372713, v37
	v_mul_f32_e32 v38, 0x3fcc422a, v37
	v_fma_f32 v39, v37, v39, 1.0
	v_mul_f32_e32 v38, v38, v39
	v_mul_f32_e32 v38, 0xbfb8aa3b, v38
	v_exp_f32_e32 v38, v38
	v_mul_f32_e32 v39, 0x3d372713, v40
	v_fma_f32 v39, v40, v39, 1.0
	v_cvt_pk_bf16_f32 v34, v34, v35
	v_add_f32_e32 v38, 1.0, v38
	v_rcp_f32_e32 v45, v38
	v_mul_f32_e32 v38, 0x3fcc422a, v40
	v_mul_f32_e32 v38, v38, v39
	v_mul_f32_e32 v39, 0x3fcc422a, v42
	v_pk_mul_f32 v[36:37], v[36:37], v[44:45]
	v_mul_f32_e32 v44, 0x3d372713, v42
	v_fma_f32 v44, v42, v44, 1.0
	v_mul_f32_e32 v39, v39, v44
	v_mul_f32_e32 v39, 0xbfb8aa3b, v39
	v_exp_f32_e32 v39, v39
	v_mul_f32_e32 v45, 0x3d372713, v41
	v_fma_f32 v45, v41, v45, 1.0
	v_mul_f32_e32 v38, 0xbfb8aa3b, v38
	v_add_f32_e32 v39, 1.0, v39
	v_rcp_f32_e32 v44, v39
	v_mul_f32_e32 v39, 0x3fcc422a, v41
	v_mul_f32_e32 v39, v39, v45
	v_mul_f32_e32 v39, 0xbfb8aa3b, v39
	v_exp_f32_e32 v38, v38
	v_exp_f32_e32 v39, v39
	v_cvt_pk_bf16_f32 v36, v36, v37
	v_add_f32_e32 v38, 1.0, v38
	v_add_f32_e32 v39, 1.0, v39
	v_rcp_f32_e32 v38, v38
	v_rcp_f32_e32 v39, v39
	s_nop 0
	v_pk_mul_f32 v[38:39], v[40:41], v[38:39]
	v_mul_f32_e32 v41, 0x3d372713, v43
	v_mul_f32_e32 v40, 0x3fcc422a, v43
	v_fma_f32 v41, v43, v41, 1.0
	v_mul_f32_e32 v40, v40, v41
	v_mul_f32_e32 v40, 0xbfb8aa3b, v40
	v_exp_f32_e32 v40, v40
	v_cvt_pk_bf16_f32 v35, v38, v39
	v_mov_b32_e32 v39, v99
	v_add_f32_e32 v40, 1.0, v40
	v_rcp_f32_e32 v45, v40
	s_nop 0
	v_pk_mul_f32 v[40:41], v[42:43], v[44:45]
	v_or_b32_e32 v42, v118, v74
	v_lshlrev_b32_e32 v38, 10, v42
	v_lshl_add_u64 v[38:39], s[14:15], 0, v[38:39]
	v_lshl_add_u64 v[38:39], v[38:39], 0, s[12:13]
	v_cvt_pk_bf16_f32 v37, v40, v41
	v_lshl_add_u64 v[38:39], v[38:39], 0, v[164:165]
	global_store_dwordx4 v[38:39], v[34:37], off
	s_nop 1
	v_lshl_add_u64 v[34:35], v[108:109], 0, v[98:99]
	v_lshl_add_u64 v[34:35], v[34:35], 0, v[164:165]
	v_mov_b64_e32 v[34:35], v[232:233]
	v_mov_b64_e32 v[36:37], v[234:235]
	v_lshlrev_b32_e32 v38, 16, v34
	v_and_b32_e32 v39, 0xffff0000, v34
	v_lshlrev_b32_e32 v34, 16, v35
	v_and_b32_e32 v35, 0xffff0000, v35
	v_lshlrev_b32_e32 v40, 16, v36
	v_and_b32_e32 v41, 0xffff0000, v36
	v_pk_fma_f32 v[30:31], v[62:63], v[38:39], v[30:31]
	v_lshlrev_b32_e32 v36, 16, v37
	v_and_b32_e32 v37, 0xffff0000, v37
	v_pk_fma_f32 v[32:33], v[64:65], v[34:35], v[32:33]
	v_pk_fma_f32 v[26:27], v[58:59], v[40:41], v[26:27]
	v_mul_f32_e32 v35, 0x3d372713, v30
	v_pk_fma_f32 v[28:29], v[60:61], v[36:37], v[28:29]
; __device__ __forceinline__ float fast_sigmoid(float v) { return __builtin_amdgcn_rcpf(1.0f + __builtin_amdgcn_exp2f(-v * LOG2E)); }
; __device__ __forceinline__ u32x4 pack8(f32x4 a, f32x4 b) { u32x4 w; w.x = cvt_pk_bf16(a[0], a[1]); w.y = cvt_pk_bf16(a[2], a[3]); w.z = cvt_pk_bf16(b[0], b[1]); w.w = cvt_pk_bf16(b[2], b[3]); return w; }
; __device__ __forceinline__ void unpack8(u32x4 w, f32x4& a, f32x4& b) { a = (f32x4){bf_lo(w.x), bf_hi(w.x), bf_lo(w.y), bf_hi(w.y)}; b = (f32x4){bf_lo(w.z), bf_hi(w.z), bf_lo(w.w), bf_hi(w.w)}; }
;     __device__ __forceinline__ void operator()(Acc& acc, const Unit& u, int wr, int wc, int fr, int fq) const {
;         const int R0 = u.pm * BM + wr * 64 + fr, gg = u.pm >> 2, nb = (u.pn & 1) * BM + wc * 64 + 8 * fq;
; #pragma unroll
;         for (int bj = 0; bj < 2; ++bj) { const int np = nb + bj * BJ, i = np >> 4, c0 = np & 15;
;             const f32x4 d0 = *(const f32x4*)(dskip + gg * 16 + c0), d1 = *(const f32x4*)(dskip + gg * 16 + c0 + 4);
; #pragma unroll
;             for (int ai = 0; ai < 2; ++ai)
; #pragma unroll
;                 for (int m = 0; m < 4; ++m) { const int R = R0 + ai * HALF + m * 16; const int token = (R & (ROWS_G - 1)) * TCH + i;
;                     f32x4 u0, u1; unpack8(*(const u32x4*)(a2 + (size_t)R * K2 + i * 16 + c0), u0, u1);
;                     f32x4 y0 = acc[ai][bj][m][0] + d0 * u0, y1 = acc[ai][bj][m][1] + d1 * u1;
; #pragma unroll
;                     for (int e = 0; e < 4; ++e) { { const float y = y0[e]; const float t = 1.5957691216057308f * y * (1.0f + 0.044715f * y * y); y0[e] = y * fast_sigmoid(t); }
;                                                   { const float y = y1[e]; const float t = 1.5957691216057308f * y * (1.0f + 0.044715f * y * y); y1[e] = y * fast_sigmoid(t); } }
;                     *(u32x4*)(gbuf + (size_t)token * 512 + gg * 16 + c0) = pack8(y0, y1); } }
;     }
	v_mul_f32_e32 v34, 0x3fcc422a, v30
	v_fma_f32 v35, v30, v35, 1.0
	v_mul_f32_e32 v36, 0x3d372713, v26
	v_mul_f32_e32 v34, v34, v35
	v_mul_f32_e32 v35, 0x3fcc422a, v26
	v_fma_f32 v36, v26, v36, 1.0
	v_mul_f32_e32 v35, v35, v36
	v_mul_f32_e32 v35, 0xbfb8aa3b, v35
	v_exp_f32_e32 v35, v35
	v_mul_f32_e32 v37, 0x3d372713, v31
	v_fma_f32 v37, v31, v37, 1.0
	v_mul_f32_e32 v34, 0xbfb8aa3b, v34
	v_add_f32_e32 v35, 1.0, v35
	v_rcp_f32_e32 v36, v35
	v_mul_f32_e32 v35, 0x3fcc422a, v31
	v_mul_f32_e32 v35, v35, v37
	v_mul_f32_e32 v35, 0xbfb8aa3b, v35
	v_exp_f32_e32 v34, v34
	v_exp_f32_e32 v35, v35
	v_or_b32_e32 v38, v110, v74
	v_add_f32_e32 v34, 1.0, v34
	v_add_f32_e32 v35, 1.0, v35
	v_rcp_f32_e32 v34, v34
	v_rcp_f32_e32 v35, v35
	s_nop 0
	v_pk_mul_f32 v[30:31], v[30:31], v[34:35]
	v_mul_f32_e32 v35, 0x3d372713, v27
	v_mul_f32_e32 v34, 0x3fcc422a, v27
	v_fma_f32 v35, v27, v35, 1.0
	v_mul_f32_e32 v34, v34, v35
	v_mul_f32_e32 v34, 0xbfb8aa3b, v34
	v_exp_f32_e32 v34, v34
	s_nop 0
	v_add_f32_e32 v34, 1.0, v34
	v_rcp_f32_e32 v37, v34
	s_nop 0
	v_pk_mul_f32 v[34:35], v[26:27], v[36:37]
	v_mul_f32_e32 v27, 0x3d372713, v32
	v_mul_f32_e32 v26, 0x3fcc422a, v32
	v_fma_f32 v27, v32, v27, 1.0
	v_mul_f32_e32 v36, 0x3d372713, v28
	v_mul_f32_e32 v26, v26, v27
	v_mul_f32_e32 v27, 0x3fcc422a, v28
	v_fma_f32 v36, v28, v36, 1.0
	v_mul_f32_e32 v27, v27, v36
	v_mul_f32_e32 v27, 0xbfb8aa3b, v27
	v_exp_f32_e32 v27, v27
	v_mul_f32_e32 v37, 0x3d372713, v33
	v_fma_f32 v37, v33, v37, 1.0
	v_mul_f32_e32 v26, 0xbfb8aa3b, v26
	v_add_f32_e32 v27, 1.0, v27
	v_rcp_f32_e32 v36, v27
	v_mul_f32_e32 v27, 0x3fcc422a, v33
	v_mul_f32_e32 v27, v27, v37
	v_mul_f32_e32 v27, 0xbfb8aa3b, v27
	v_exp_f32_e32 v26, v26
	v_exp_f32_e32 v27, v27
	v_add_f32_e32 v26, 1.0, v26
	v_add_f32_e32 v27, 1.0, v27
	v_rcp_f32_e32 v26, v26
	v_rcp_f32_e32 v27, v27
	s_nop 0
	v_pk_mul_f32 v[32:33], v[32:33], v[26:27]
	v_mul_f32_e32 v27, 0x3d372713, v29
	v_mul_f32_e32 v26, 0x3fcc422a, v29
	v_fma_f32 v27, v29, v27, 1.0
	v_mul_f32_e32 v26, v26, v27
	v_mul_f32_e32 v26, 0xbfb8aa3b, v26
	v_exp_f32_e32 v26, v26
	v_cvt_pk_bf16_f32 v27, v32, v33
	v_add_f32_e32 v26, 1.0, v26
	v_rcp_f32_e32 v37, v26
	v_cvt_pk_bf16_f32 v26, v30, v31
	v_lshlrev_b32_e32 v30, 10, v38
	v_mov_b32_e32 v31, v99
	v_lshl_add_u64 v[30:31], s[14:15], 0, v[30:31]
	v_pk_mul_f32 v[36:37], v[28:29], v[36:37]
	v_lshl_add_u64 v[30:31], v[30:31], 0, s[12:13]
	v_cvt_pk_bf16_f32 v28, v34, v35
	v_cvt_pk_bf16_f32 v29, v36, v37
	v_lshl_add_u64 v[30:31], v[30:31], 0, v[164:165]
	global_store_dwordx4 v[30:31], v[26:29], off
	s_nop 1
	v_lshl_add_u64 v[26:27], v[100:101], 0, v[98:99]
	v_lshl_add_u64 v[26:27], v[26:27], 0, v[164:165]
	v_mov_b64_e32 v[26:27], v[184:185]
	v_mov_b64_e32 v[28:29], v[186:187]
	v_lshlrev_b32_e32 v30, 16, v26
	v_and_b32_e32 v31, 0xffff0000, v26
	v_lshlrev_b32_e32 v26, 16, v27
	v_and_b32_e32 v27, 0xffff0000, v27
	v_lshlrev_b32_e32 v32, 16, v28
	v_and_b32_e32 v33, 0xffff0000, v28
	v_pk_fma_f32 v[22:23], v[62:63], v[30:31], v[22:23]
	v_lshlrev_b32_e32 v28, 16, v29
	v_and_b32_e32 v29, 0xffff0000, v29
	v_pk_fma_f32 v[24:25], v[64:65], v[26:27], v[24:25]
	v_pk_fma_f32 v[18:19], v[58:59], v[32:33], v[18:19]
	v_mul_f32_e32 v27, 0x3d372713, v22
	v_pk_fma_f32 v[20:21], v[60:61], v[28:29], v[20:21]
	v_mul_f32_e32 v26, 0x3fcc422a, v22
	v_fma_f32 v27, v22, v27, 1.0
	v_mul_f32_e32 v28, 0x3d372713, v18
	v_mul_f32_e32 v26, v26, v27
	v_mul_f32_e32 v27, 0x3fcc422a, v18
	v_fma_f32 v28, v18, v28, 1.0
	v_mul_f32_e32 v27, v27, v28
	v_mul_f32_e32 v27, 0xbfb8aa3b, v27
	v_exp_f32_e32 v27, v27
	v_mul_f32_e32 v29, 0x3d372713, v23
	v_fma_f32 v29, v23, v29, 1.0
	v_mul_f32_e32 v26, 0xbfb8aa3b, v26
	v_add_f32_e32 v27, 1.0, v27
	v_rcp_f32_e32 v28, v27
	v_mul_f32_e32 v27, 0x3fcc422a, v23
	v_mul_f32_e32 v27, v27, v29
	v_mul_f32_e32 v27, 0xbfb8aa3b, v27
	v_exp_f32_e32 v26, v26
	v_exp_f32_e32 v27, v27
	v_or_b32_e32 v30, v102, v74
	v_add_f32_e32 v26, 1.0, v26
	v_add_f32_e32 v27, 1.0, v27
	v_rcp_f32_e32 v26, v26
	v_rcp_f32_e32 v27, v27
	s_nop 0
	v_pk_mul_f32 v[22:23], v[22:23], v[26:27]
	v_mul_f32_e32 v27, 0x3d372713, v19
	v_mul_f32_e32 v26, 0x3fcc422a, v19
	v_fma_f32 v27, v19, v27, 1.0
	v_mul_f32_e32 v26, v26, v27
	v_mul_f32_e32 v26, 0xbfb8aa3b, v26
	v_exp_f32_e32 v26, v26
	s_nop 0
	v_add_f32_e32 v26, 1.0, v26
	v_rcp_f32_e32 v29, v26
	s_nop 0
	v_pk_mul_f32 v[26:27], v[18:19], v[28:29]
	v_mul_f32_e32 v19, 0x3d372713, v24
	v_mul_f32_e32 v18, 0x3fcc422a, v24
	v_fma_f32 v19, v24, v19, 1.0
	v_mul_f32_e32 v28, 0x3d372713, v20
	v_mul_f32_e32 v18, v18, v19
	v_mul_f32_e32 v19, 0x3fcc422a, v20
	v_fma_f32 v28, v20, v28, 1.0
	v_mul_f32_e32 v19, v19, v28
	v_mul_f32_e32 v19, 0xbfb8aa3b, v19
	v_exp_f32_e32 v19, v19
	v_mul_f32_e32 v29, 0x3d372713, v25
	v_fma_f32 v29, v25, v29, 1.0
	v_mul_f32_e32 v18, 0xbfb8aa3b, v18
	v_add_f32_e32 v19, 1.0, v19
	v_rcp_f32_e32 v28, v19
	v_mul_f32_e32 v19, 0x3fcc422a, v25
	v_mul_f32_e32 v19, v19, v29
	v_mul_f32_e32 v19, 0xbfb8aa3b, v19
	v_exp_f32_e32 v18, v18
	v_exp_f32_e32 v19, v19
	v_add_f32_e32 v18, 1.0, v18
	v_add_f32_e32 v19, 1.0, v19
	v_rcp_f32_e32 v18, v18
	v_rcp_f32_e32 v19, v19
	s_nop 0
	v_pk_mul_f32 v[24:25], v[24:25], v[18:19]
	v_mul_f32_e32 v19, 0x3d372713, v21
	v_mul_f32_e32 v18, 0x3fcc422a, v21
	v_fma_f32 v19, v21, v19, 1.0
	v_mul_f32_e32 v18, v18, v19
	v_mul_f32_e32 v18, 0xbfb8aa3b, v18
	v_exp_f32_e32 v18, v18
	v_cvt_pk_bf16_f32 v19, v24, v25
	v_add_f32_e32 v18, 1.0, v18
	v_rcp_f32_e32 v29, v18
	v_cvt_pk_bf16_f32 v18, v22, v23
	v_lshlrev_b32_e32 v22, 10, v30
	v_mov_b32_e32 v23, v99
	v_lshl_add_u64 v[22:23], s[14:15], 0, v[22:23]
	v_pk_mul_f32 v[28:29], v[20:21], v[28:29]
	v_lshl_add_u64 v[22:23], v[22:23], 0, s[12:13]
	v_cvt_pk_bf16_f32 v20, v26, v27
; __device__ __forceinline__ float fast_sigmoid(float v) { return __builtin_amdgcn_rcpf(1.0f + __builtin_amdgcn_exp2f(-v * LOG2E)); }
; __device__ __forceinline__ u32x4 pack8(f32x4 a, f32x4 b) { u32x4 w; w.x = cvt_pk_bf16(a[0], a[1]); w.y = cvt_pk_bf16(a[2], a[3]); w.z = cvt_pk_bf16(b[0], b[1]); w.w = cvt_pk_bf16(b[2], b[3]); return w; }
; __device__ __forceinline__ void unpack8(u32x4 w, f32x4& a, f32x4& b) { a = (f32x4){bf_lo(w.x), bf_hi(w.x), bf_lo(w.y), bf_hi(w.y)}; b = (f32x4){bf_lo(w.z), bf_hi(w.z), bf_lo(w.w), bf_hi(w.w)}; }
; #define PG8_BAR __builtin_amdgcn_s_barrier()
; template <class Epi, class Sched>
; __device__ __forceinline__ void gemm_phase(LAS unsigned char* lds, const Gemm g, const Sched& S, const Epi& E) {
;     ...
;         if (!has_next) break;
;         if (!E.keep(cur)) {
;             bf16x8 zf = {0, 0, 0, 0, 0, 0, 0, 0}; asm volatile("" : "+v"(zf));
; #pragma unroll
;             for (int a = 0; a < 2; ++a)
; #pragma unroll
;                 for (int b = 0; b < 2; ++b)
; #pragma unroll
;                     for (int m = 0; m < 4; ++m)
; #pragma unroll
;                         for (int n = 0; n < 2; ++n) acc[a][b][m][n] = __builtin_amdgcn_mfma_f32_16x16x32_bf16(zf, zf, (f32x4){0.f, 0.f, 0.f, 0.f}, 0, 0, 0);
;         }
;         cur = nxt; cA = nA; cB = nB; ++ui;
;         if (wr == 1) PG8_BAR;
;     __device__ __forceinline__ void operator()(Acc& acc, const Unit& u, int wr, int wc, int fr, int fq) const {
;     ...
;                     f32x4 u0, u1; unpack8(*(const u32x4*)(a2 + (size_t)R * K2 + i * 16 + c0), u0, u1);
;                     f32x4 y0 = acc[ai][bj][m][0] + d0 * u0, y1 = acc[ai][bj][m][1] + d1 * u1;
; #pragma unroll
;                     for (int e = 0; e < 4; ++e) { { const float y = y0[e]; const float t = 1.5957691216057308f * y * (1.0f + 0.044715f * y * y); y0[e] = y * fast_sigmoid(t); }
;                                                   { const float y = y1[e]; const float t = 1.5957691216057308f * y * (1.0f + 0.044715f * y * y); y1[e] = y * fast_sigmoid(t); } }
;                     *(u32x4*)(gbuf + (size_t)token * 512 + gg * 16 + c0) = pack8(y0, y1); } }
	v_cvt_pk_bf16_f32 v21, v28, v29
	v_lshl_add_u64 v[22:23], v[22:23], 0, v[164:165]
	global_store_dwordx4 v[22:23], v[18:21], off
	s_nop 1
	v_lshl_add_u64 v[18:19], v[90:91], 0, v[98:99]
	v_lshl_add_u64 v[18:19], v[18:19], 0, v[164:165]
	v_mov_b64_e32 v[18:19], v[188:189]
	v_mov_b64_e32 v[20:21], v[190:191]
	v_lshlrev_b32_e32 v22, 16, v18
	v_and_b32_e32 v23, 0xffff0000, v18
	v_lshlrev_b32_e32 v18, 16, v19
	v_and_b32_e32 v19, 0xffff0000, v19
	v_lshlrev_b32_e32 v24, 16, v20
	v_and_b32_e32 v25, 0xffff0000, v20
	v_pk_fma_f32 v[14:15], v[62:63], v[22:23], v[14:15]
	v_lshlrev_b32_e32 v20, 16, v21
	v_and_b32_e32 v21, 0xffff0000, v21
	v_pk_fma_f32 v[16:17], v[64:65], v[18:19], v[16:17]
	v_pk_fma_f32 v[10:11], v[58:59], v[24:25], v[10:11]
	v_mul_f32_e32 v19, 0x3d372713, v14
	v_pk_fma_f32 v[12:13], v[60:61], v[20:21], v[12:13]
	v_mul_f32_e32 v18, 0x3fcc422a, v14
	v_fma_f32 v19, v14, v19, 1.0
	v_mul_f32_e32 v20, 0x3d372713, v10
	v_mul_f32_e32 v18, v18, v19
	v_mul_f32_e32 v19, 0x3fcc422a, v10
	v_fma_f32 v20, v10, v20, 1.0
	v_mul_f32_e32 v19, v19, v20
	v_mul_f32_e32 v19, 0xbfb8aa3b, v19
	v_exp_f32_e32 v19, v19
	v_mul_f32_e32 v21, 0x3d372713, v15
	v_fma_f32 v21, v15, v21, 1.0
	v_mul_f32_e32 v18, 0xbfb8aa3b, v18
	v_add_f32_e32 v19, 1.0, v19
	v_rcp_f32_e32 v20, v19
	v_mul_f32_e32 v19, 0x3fcc422a, v15
	v_mul_f32_e32 v19, v19, v21
	v_mul_f32_e32 v19, 0xbfb8aa3b, v19
	v_exp_f32_e32 v18, v18
	v_exp_f32_e32 v19, v19
	v_or_b32_e32 v22, v92, v74
	v_add_f32_e32 v18, 1.0, v18
	v_add_f32_e32 v19, 1.0, v19
	v_rcp_f32_e32 v18, v18
	v_rcp_f32_e32 v19, v19
	s_nop 0
	v_pk_mul_f32 v[14:15], v[14:15], v[18:19]
	v_mul_f32_e32 v19, 0x3d372713, v11
	v_mul_f32_e32 v18, 0x3fcc422a, v11
	v_fma_f32 v19, v11, v19, 1.0
	v_mul_f32_e32 v18, v18, v19
	v_mul_f32_e32 v18, 0xbfb8aa3b, v18
	v_exp_f32_e32 v18, v18
	s_nop 0
	v_add_f32_e32 v18, 1.0, v18
	v_rcp_f32_e32 v21, v18
	s_nop 0
	v_pk_mul_f32 v[18:19], v[10:11], v[20:21]
	v_mul_f32_e32 v11, 0x3d372713, v16
	v_mul_f32_e32 v10, 0x3fcc422a, v16
	v_fma_f32 v11, v16, v11, 1.0
	v_mul_f32_e32 v20, 0x3d372713, v12
	v_mul_f32_e32 v10, v10, v11
	v_mul_f32_e32 v11, 0x3fcc422a, v12
	v_fma_f32 v20, v12, v20, 1.0
	v_mul_f32_e32 v11, v11, v20
	v_mul_f32_e32 v11, 0xbfb8aa3b, v11
	v_exp_f32_e32 v11, v11
	v_mul_f32_e32 v21, 0x3d372713, v17
	v_fma_f32 v21, v17, v21, 1.0
	v_mul_f32_e32 v10, 0xbfb8aa3b, v10
	v_add_f32_e32 v11, 1.0, v11
	v_rcp_f32_e32 v20, v11
	v_mul_f32_e32 v11, 0x3fcc422a, v17
	v_mul_f32_e32 v11, v11, v21
	v_mul_f32_e32 v11, 0xbfb8aa3b, v11
	v_exp_f32_e32 v10, v10
	v_exp_f32_e32 v11, v11
	v_add_f32_e32 v10, 1.0, v10
	v_add_f32_e32 v11, 1.0, v11
	v_rcp_f32_e32 v10, v10
	v_rcp_f32_e32 v11, v11
	s_nop 0
	v_pk_mul_f32 v[16:17], v[16:17], v[10:11]
	v_mul_f32_e32 v11, 0x3d372713, v13
	v_mul_f32_e32 v10, 0x3fcc422a, v13
	v_fma_f32 v11, v13, v11, 1.0
	v_mul_f32_e32 v10, v10, v11
	v_mul_f32_e32 v10, 0xbfb8aa3b, v10
	v_exp_f32_e32 v10, v10
	v_cvt_pk_bf16_f32 v11, v16, v17
	v_add_f32_e32 v10, 1.0, v10
	v_rcp_f32_e32 v21, v10
	v_cvt_pk_bf16_f32 v10, v14, v15
	v_lshlrev_b32_e32 v14, 10, v22
	v_mov_b32_e32 v15, v99
	v_lshl_add_u64 v[14:15], s[14:15], 0, v[14:15]
	v_pk_mul_f32 v[20:21], v[12:13], v[20:21]
	v_lshl_add_u64 v[14:15], v[14:15], 0, s[12:13]
	v_cvt_pk_bf16_f32 v12, v18, v19
	v_cvt_pk_bf16_f32 v13, v20, v21
	v_lshl_add_u64 v[14:15], v[14:15], 0, v[164:165]
	global_store_dwordx4 v[14:15], v[10:13], off
	s_nop 1
	v_lshl_add_u64 v[10:11], v[82:83], 0, v[98:99]
	v_lshl_add_u64 v[10:11], v[10:11], 0, v[164:165]
	v_mov_b64_e32 v[10:11], v[192:193]
	v_mov_b64_e32 v[12:13], v[194:195]
	v_lshlrev_b32_e32 v14, 16, v10
	v_and_b32_e32 v15, 0xffff0000, v10
	v_lshlrev_b32_e32 v10, 16, v11
	v_and_b32_e32 v11, 0xffff0000, v11
	v_lshlrev_b32_e32 v16, 16, v12
	v_and_b32_e32 v17, 0xffff0000, v12
	v_pk_fma_f32 v[6:7], v[62:63], v[14:15], v[6:7]
	v_lshlrev_b32_e32 v12, 16, v13
	v_and_b32_e32 v13, 0xffff0000, v13
	v_pk_fma_f32 v[8:9], v[64:65], v[10:11], v[8:9]
	v_pk_fma_f32 v[2:3], v[58:59], v[16:17], v[2:3]
	v_mul_f32_e32 v11, 0x3d372713, v6
	v_pk_fma_f32 v[4:5], v[60:61], v[12:13], v[4:5]
	v_mul_f32_e32 v10, 0x3fcc422a, v6
	v_fma_f32 v11, v6, v11, 1.0
	v_mul_f32_e32 v12, 0x3d372713, v2
	v_mul_f32_e32 v10, v10, v11
	v_mul_f32_e32 v11, 0x3fcc422a, v2
	v_fma_f32 v12, v2, v12, 1.0
	v_mul_f32_e32 v11, v11, v12
	v_mul_f32_e32 v11, 0xbfb8aa3b, v11
	v_exp_f32_e32 v11, v11
	v_mul_f32_e32 v13, 0x3d372713, v7
	v_fma_f32 v13, v7, v13, 1.0
	v_mul_f32_e32 v10, 0xbfb8aa3b, v10
	v_add_f32_e32 v11, 1.0, v11
	v_rcp_f32_e32 v12, v11
	v_mul_f32_e32 v11, 0x3fcc422a, v7
	v_mul_f32_e32 v11, v11, v13
	v_mul_f32_e32 v11, 0xbfb8aa3b, v11
	v_exp_f32_e32 v10, v10
	v_exp_f32_e32 v11, v11
	v_or_b32_e32 v14, v84, v74
	v_lshlrev_b32_e32 v98, 10, v14
	v_add_f32_e32 v10, 1.0, v10
	v_add_f32_e32 v11, 1.0, v11
	v_rcp_f32_e32 v10, v10
	v_rcp_f32_e32 v11, v11
	s_nop 0
	v_pk_mul_f32 v[6:7], v[6:7], v[10:11]
	v_mul_f32_e32 v11, 0x3d372713, v3
	v_mul_f32_e32 v10, 0x3fcc422a, v3
	v_fma_f32 v11, v3, v11, 1.0
	v_mul_f32_e32 v10, v10, v11
	v_mul_f32_e32 v10, 0xbfb8aa3b, v10
	v_exp_f32_e32 v10, v10
	s_nop 0
	v_add_f32_e32 v10, 1.0, v10
	v_rcp_f32_e32 v13, v10
	s_nop 0
	v_pk_mul_f32 v[10:11], v[2:3], v[12:13]
	v_mul_f32_e32 v3, 0x3d372713, v8
	v_mul_f32_e32 v2, 0x3fcc422a, v8
	v_fma_f32 v3, v8, v3, 1.0
	v_mul_f32_e32 v12, 0x3d372713, v4
	v_mul_f32_e32 v2, v2, v3
	v_mul_f32_e32 v3, 0x3fcc422a, v4
	v_fma_f32 v12, v4, v12, 1.0
	v_mul_f32_e32 v3, v3, v12
	v_mul_f32_e32 v3, 0xbfb8aa3b, v3
	v_exp_f32_e32 v3, v3
	v_mul_f32_e32 v13, 0x3d372713, v9
	v_fma_f32 v13, v9, v13, 1.0
	v_mul_f32_e32 v2, 0xbfb8aa3b, v2
	v_add_f32_e32 v3, 1.0, v3
	v_rcp_f32_e32 v12, v3
	v_mul_f32_e32 v3, 0x3fcc422a, v9
	v_mul_f32_e32 v3, v3, v13
	v_mul_f32_e32 v3, 0xbfb8aa3b, v3
	v_exp_f32_e32 v2, v2
	v_exp_f32_e32 v3, v3
	v_add_f32_e32 v2, 1.0, v2
	v_add_f32_e32 v3, 1.0, v3
	v_rcp_f32_e32 v2, v2
	v_rcp_f32_e32 v3, v3
	s_nop 0
	v_pk_mul_f32 v[8:9], v[8:9], v[2:3]
	v_mul_f32_e32 v3, 0x3d372713, v5
	v_mul_f32_e32 v2, 0x3fcc422a, v5
	v_fma_f32 v3, v5, v3, 1.0
	v_mul_f32_e32 v2, v2, v3
	v_mul_f32_e32 v2, 0xbfb8aa3b, v2
	v_exp_f32_e32 v2, v2
	v_cvt_pk_bf16_f32 v3, v8, v9
	v_add_f32_e32 v2, 1.0, v2
	v_rcp_f32_e32 v13, v2
	v_cvt_pk_bf16_f32 v2, v6, v7
	v_lshl_add_u64 v[6:7], s[14:15], 0, v[98:99]
	v_lshl_add_u64 v[6:7], v[6:7], 0, s[12:13]
	v_pk_mul_f32 v[12:13], v[4:5], v[12:13]
	v_cvt_pk_bf16_f32 v4, v10, v11
	v_cvt_pk_bf16_f32 v5, v12, v13
	v_lshl_add_u64 v[6:7], v[6:7], 0, v[164:165]
	global_store_dwordx4 v[6:7], v[2:5], off
	s_cbranch_vccnz .LBB0_427
	v_mov_b32_e32 v98, v99
	v_mov_b32_e32 v100, v99
	v_mov_b32_e32 v101, v99
	v_mov_b64_e32 v[2:3], v[98:99]
	v_mov_b64_e32 v[4:5], v[100:101]
	s_andn2_b64 vcc, exec, s[0:1]
	s_nop 0
	v_mfma_f32_16x16x32_bf16 v[2:5], v[2:5], v[2:5], 0
	s_cbranch_vccnz .LBB0_426
	s_barrier
	s_branch .LBB0_426
